# ret_scan: the 128 state-decay multiplies moved from the head of the state-update section into the load-wait shadow of the rkT staging section
# speedup vs baseline: 1.0052x; 1.0052x over previous
.LBB0_327:
	v_mov_b32_e32 v130, s67
	v_mov_b32_e32 v131, s66
	v_cndmask_b32_e32 v130, v130, v131, vcc
	v_lshl_add_u32 v168, v130, 7, v155
	v_mov_b32_e32 v153, v161
	v_mov_b32_e32 v192, v181
	v_mov_b32_e32 v190, v183
	v_mov_b32_e32 v191, v182
	v_mov_b32_e32 v166, v157
	v_mov_b32_e32 v130, v186
	v_mov_b32_e32 v131, v187
	v_ashrrev_i32_e32 v169, 31, v168
	v_readfirstlane_b32 s64, v130
	v_readfirstlane_b32 s65, v131
	v_lshlrev_b64 v[130:131], 11, v[168:169]
	v_mov_b32_e32 v167, v189
	s_barrier
	v_lshl_add_u64 v[244:245], s[64:65], 0, v[130:131]
	v_lshl_add_u64 v[244:245], v[244:245], 0, v[0:1]
	s_mov_b32 s6, 0xc640000
	s_mov_b32 s7, 0
	v_lshl_add_u64 v[244:245], v[244:245], 0, s[6:7]
	v_and_b32_e32 v247, 0xff, v189
	v_lshrrev_b32_e32 v248, 5, v247
	v_and_b32_e32 v247, 31, v247
	v_add_u32_e32 v249, 64, v248
	v_lshlrev_b32_e32 v249, 11, v249
	v_lshl_add_u32 v242, v247, 4, v249
	v_mov_b32_e32 v243, 0
	v_lshl_add_u64 v[242:243], v[244:245], 0, v[242:243]
	v_lshrrev_b32_e32 v249, 1, v248
	v_add_u32_e32 v249, 32, v249
	v_mul_u32_u24_e32 v249, 0x410, v249
	v_and_b32_e32 v248, 1, v248
	v_lshl_add_u32 v249, v248, 9, v249
	v_lshl_add_u32 v249, v247, 4, v249
	v_add_u32_e32 v246, v149, v249
	s_mov_b32 s6, 0x4000
	global_load_dwordx4 v[130:133], v[242:243], off
	v_lshl_add_u64 v[242:243], v[242:243], 0, s[6:7]
	global_load_dwordx4 v[134:137], v[242:243], off
	v_lshl_add_u64 v[242:243], v[242:243], 0, s[6:7]
	global_load_dwordx4 v[138:141], v[242:243], off
	v_lshl_add_u64 v[242:243], v[242:243], 0, s[6:7]
	global_load_dwordx4 v[142:145], v[242:243], off
	v_lshl_add_u64 v[242:243], v[242:243], 0, s[6:7]
	global_load_dwordx4 v[170:173], v[242:243], off
	v_lshl_add_u64 v[242:243], v[242:243], 0, s[6:7]
	global_load_dwordx4 v[194:197], v[242:243], off
	v_lshl_add_u64 v[242:243], v[242:243], 0, s[6:7]
	global_load_dwordx4 v[218:221], v[242:243], off
	v_lshl_add_u64 v[242:243], v[242:243], 0, s[6:7]
	global_load_dwordx4 v[222:225], v[242:243], off
	v_bfe_u32 v248, v189, 6, 2
	v_lshlrev_b32_e32 v248, 4, v248
	v_bfe_u32 v249, v189, 5, 1
	v_add_u32_e32 v248, v248, v249
	v_lshlrev_b32_e32 v248, 11, v248
	v_and_b32_e32 v249, 31, v189
	v_lshl_add_u32 v248, v249, 4, v248
	v_mov_b32_e32 v249, 0
	v_lshl_add_u64 v[244:245], v[244:245], 0, v[248:249]
	v_readfirstlane_b32 s6, v149
	v_readfirstlane_b32 s7, v189
	s_nop 3
	s_bfe_u32 s7, s7, 0x20006
	s_mul_i32 s7, s7, 0x2080
	s_add_u32 s6, s6, s7
	s_mov_b32 m0, s6
	s_mov_b32 s6, 0x1000
	s_mov_b32 s7, 0
	global_load_lds_dwordx4 v[244:245], off
	s_add_u32 m0, m0, 0x410
	v_lshl_add_u64 v[244:245], v[244:245], 0, s[6:7]
	global_load_lds_dwordx4 v[244:245], off
	s_add_u32 m0, m0, 0x410
	v_lshl_add_u64 v[244:245], v[244:245], 0, s[6:7]
	global_load_lds_dwordx4 v[244:245], off
	s_add_u32 m0, m0, 0x410
	v_lshl_add_u64 v[244:245], v[244:245], 0, s[6:7]
	global_load_lds_dwordx4 v[244:245], off
	s_add_u32 m0, m0, 0x410
	v_lshl_add_u64 v[244:245], v[244:245], 0, s[6:7]
	global_load_lds_dwordx4 v[244:245], off
	s_add_u32 m0, m0, 0x410
	v_lshl_add_u64 v[244:245], v[244:245], 0, s[6:7]
	global_load_lds_dwordx4 v[244:245], off
	s_add_u32 m0, m0, 0x410
	v_lshl_add_u64 v[244:245], v[244:245], 0, s[6:7]
	global_load_lds_dwordx4 v[244:245], off
	s_add_u32 m0, m0, 0x410
	v_lshl_add_u64 v[244:245], v[244:245], 0, s[6:7]
	global_load_lds_dwordx4 v[244:245], off
	s_waitcnt vmcnt(15)
	ds_write2_b64 v246, v[130:131], v[132:133] offset1:1
	s_waitcnt vmcnt(14)
	v_add_u32_e32 v247, 0x1040, v246
	ds_write2_b64 v247, v[134:135], v[136:137] offset1:1
	s_waitcnt vmcnt(13)
	v_add_u32_e32 v247, 0x2080, v246
	ds_write2_b64 v247, v[138:139], v[140:141] offset1:1
	s_waitcnt vmcnt(12)
	v_add_u32_e32 v247, 0x30c0, v246
	ds_write2_b64 v247, v[142:143], v[144:145] offset1:1
	s_waitcnt vmcnt(11)
	v_add_u32_e32 v247, 0x4100, v246
	ds_write2_b64 v247, v[170:171], v[172:173] offset1:1
	s_waitcnt vmcnt(10)
	v_add_u32_e32 v247, 0x5140, v246
	ds_write2_b64 v247, v[194:195], v[196:197] offset1:1
	s_waitcnt vmcnt(9)
	v_add_u32_e32 v247, 0x6180, v246
	ds_write2_b64 v247, v[218:219], v[220:221] offset1:1
	s_waitcnt vmcnt(8)
	v_add_u32_e32 v247, 0x71c0, v246
	ds_write2_b64 v247, v[222:223], v[224:225] offset1:1
	v_lshl_add_u64 v[210:211], s[64:65], 0, v[162:163]
	s_waitcnt vmcnt(0)
	s_waitcnt lgkmcnt(0)
	s_barrier
	v_ashrrev_i32_e32 v167, 31, v166
	v_lshl_add_u64 v[130:131], v[166:167], 1, v[210:211]
	s_mov_b64 s[6:7], 0x8640000
	v_lshl_add_u64 v[170:171], v[130:131], 0, s[6:7]
	v_add_u32_e32 v250, 0x4000, v178
	ds_read2_b64 v[194:197], v178 offset0:0 offset1:2
	ds_read2_b64 v[218:221], v250 offset0:32 offset1:34
	ds_read2_b64 v[222:225], v178 offset0:4 offset1:6
	ds_read2_b64 v[226:229], v250 offset0:36 offset1:38
	s_nop 0
	v_cvt_pk_bf16_f32 v230, v2, v3
	v_cvt_pk_bf16_f32 v231, v4, v5
	v_cvt_pk_bf16_f32 v232, v6, v7
	v_cvt_pk_bf16_f32 v233, v8, v9
	s_waitcnt lgkmcnt(2)
	s_nop 1
	v_mfma_f32_32x32x16_bf16 v[130:145], v[194:197], v[230:233], 0
	v_mfma_f32_32x32x16_bf16 v[234:249], v[218:221], v[230:233], 0
	ds_read2_b64 v[194:197], v178 offset0:8 offset1:10
	ds_read2_b64 v[218:221], v250 offset0:40 offset1:42
	s_nop 0
	v_cvt_pk_bf16_f32 v230, v10, v11
	v_cvt_pk_bf16_f32 v231, v12, v13
	v_cvt_pk_bf16_f32 v232, v14, v15
	v_cvt_pk_bf16_f32 v233, v16, v17
	s_waitcnt lgkmcnt(2)
	s_nop 1
	v_mfma_f32_32x32x16_bf16 v[130:145], v[222:225], v[230:233], v[130:145]
	v_mfma_f32_32x32x16_bf16 v[234:249], v[226:229], v[230:233], v[234:249]
	ds_read2_b64 v[222:225], v178 offset0:12 offset1:14
	ds_read2_b64 v[226:229], v250 offset0:44 offset1:46
	s_nop 0
	v_cvt_pk_bf16_f32 v230, v18, v19
	v_cvt_pk_bf16_f32 v231, v20, v21
	v_cvt_pk_bf16_f32 v232, v22, v23
	v_cvt_pk_bf16_f32 v233, v24, v25
	s_waitcnt lgkmcnt(2)
	s_nop 1
	v_mfma_f32_32x32x16_bf16 v[130:145], v[194:197], v[230:233], v[130:145]
	v_mfma_f32_32x32x16_bf16 v[234:249], v[218:221], v[230:233], v[234:249]
	ds_read2_b64 v[194:197], v178 offset0:16 offset1:18
	ds_read2_b64 v[218:221], v250 offset0:48 offset1:50
	s_nop 0
	v_cvt_pk_bf16_f32 v230, v26, v27
	v_cvt_pk_bf16_f32 v231, v28, v29
	v_cvt_pk_bf16_f32 v232, v30, v31
	v_cvt_pk_bf16_f32 v233, v32, v33
	s_waitcnt lgkmcnt(2)
	s_nop 1
	v_mfma_f32_32x32x16_bf16 v[130:145], v[222:225], v[230:233], v[130:145]
	v_mfma_f32_32x32x16_bf16 v[234:249], v[226:229], v[230:233], v[234:249]
	ds_read2_b64 v[222:225], v178 offset0:20 offset1:22
	ds_read2_b64 v[226:229], v250 offset0:52 offset1:54
	s_nop 0
	v_cvt_pk_bf16_f32 v230, v34, v35
	v_cvt_pk_bf16_f32 v231, v36, v37
	v_cvt_pk_bf16_f32 v232, v38, v39
	v_cvt_pk_bf16_f32 v233, v40, v41
	s_waitcnt lgkmcnt(2)
	s_nop 1
	v_mfma_f32_32x32x16_bf16 v[130:145], v[194:197], v[230:233], v[130:145]
	v_mfma_f32_32x32x16_bf16 v[234:249], v[218:221], v[230:233], v[234:249]
	ds_read2_b64 v[194:197], v178 offset0:24 offset1:26
	ds_read2_b64 v[218:221], v250 offset0:56 offset1:58
	s_nop 0
	v_cvt_pk_bf16_f32 v230, v42, v43
	v_cvt_pk_bf16_f32 v231, v44, v45
	v_cvt_pk_bf16_f32 v232, v46, v47
	v_cvt_pk_bf16_f32 v233, v48, v49
	s_waitcnt lgkmcnt(2)
	s_nop 1
	v_mfma_f32_32x32x16_bf16 v[130:145], v[222:225], v[230:233], v[130:145]
	v_mfma_f32_32x32x16_bf16 v[234:249], v[226:229], v[230:233], v[234:249]
	ds_read2_b64 v[222:225], v178 offset0:28 offset1:30
	ds_read2_b64 v[226:229], v250 offset0:60 offset1:62
	s_nop 0
	v_cvt_pk_bf16_f32 v230, v50, v51
	v_cvt_pk_bf16_f32 v231, v52, v53
	v_cvt_pk_bf16_f32 v232, v54, v55
	v_cvt_pk_bf16_f32 v233, v56, v57
	s_waitcnt lgkmcnt(2)
	s_nop 1
	v_mfma_f32_32x32x16_bf16 v[130:145], v[194:197], v[230:233], v[130:145]
	v_mfma_f32_32x32x16_bf16 v[234:249], v[218:221], v[230:233], v[234:249]
	ds_read2_b64 v[194:197], v178 offset0:32 offset1:34
	ds_read2_b64 v[218:221], v250 offset0:64 offset1:66
	s_nop 0
	v_cvt_pk_bf16_f32 v230, v58, v59
	v_cvt_pk_bf16_f32 v231, v60, v61
	v_cvt_pk_bf16_f32 v232, v62, v63
	v_cvt_pk_bf16_f32 v233, v64, v65
	s_waitcnt lgkmcnt(2)
	s_nop 1
	v_mfma_f32_32x32x16_bf16 v[130:145], v[222:225], v[230:233], v[130:145]
	v_mfma_f32_32x32x16_bf16 v[234:249], v[226:229], v[230:233], v[234:249]
	ds_read2_b64 v[222:225], v178 offset0:36 offset1:38
	ds_read2_b64 v[226:229], v250 offset0:68 offset1:70
	s_nop 0
	v_cvt_pk_bf16_f32 v230, v66, v67
	v_cvt_pk_bf16_f32 v231, v68, v69
	v_cvt_pk_bf16_f32 v232, v70, v71
	v_cvt_pk_bf16_f32 v233, v72, v73
	s_waitcnt lgkmcnt(2)
	s_nop 1
	v_mfma_f32_32x32x16_bf16 v[130:145], v[194:197], v[230:233], v[130:145]
	v_mfma_f32_32x32x16_bf16 v[234:249], v[218:221], v[230:233], v[234:249]
	ds_read2_b64 v[194:197], v178 offset0:40 offset1:42
	ds_read2_b64 v[218:221], v250 offset0:72 offset1:74
	s_nop 0
	v_cvt_pk_bf16_f32 v230, v74, v75
	v_cvt_pk_bf16_f32 v231, v76, v77
	v_cvt_pk_bf16_f32 v232, v78, v79
	v_cvt_pk_bf16_f32 v233, v80, v81
	s_waitcnt lgkmcnt(2)
	s_nop 1
	v_mfma_f32_32x32x16_bf16 v[130:145], v[222:225], v[230:233], v[130:145]
	v_mfma_f32_32x32x16_bf16 v[234:249], v[226:229], v[230:233], v[234:249]
	ds_read2_b64 v[222:225], v178 offset0:44 offset1:46
	ds_read2_b64 v[226:229], v250 offset0:76 offset1:78
	s_nop 0
	v_cvt_pk_bf16_f32 v230, v82, v83
	v_cvt_pk_bf16_f32 v231, v84, v85
	v_cvt_pk_bf16_f32 v232, v86, v87
	v_cvt_pk_bf16_f32 v233, v88, v89
	s_waitcnt lgkmcnt(2)
	s_nop 1
	v_mfma_f32_32x32x16_bf16 v[130:145], v[194:197], v[230:233], v[130:145]
	v_mfma_f32_32x32x16_bf16 v[234:249], v[218:221], v[230:233], v[234:249]
	ds_read2_b64 v[194:197], v178 offset0:48 offset1:50
	ds_read2_b64 v[218:221], v250 offset0:80 offset1:82
	s_nop 0
	v_cvt_pk_bf16_f32 v230, v90, v91
	v_cvt_pk_bf16_f32 v231, v92, v93
	v_cvt_pk_bf16_f32 v232, v94, v95
	v_cvt_pk_bf16_f32 v233, v96, v97
	s_waitcnt lgkmcnt(2)
	s_nop 1
	v_mfma_f32_32x32x16_bf16 v[130:145], v[222:225], v[230:233], v[130:145]
	v_mfma_f32_32x32x16_bf16 v[234:249], v[226:229], v[230:233], v[234:249]
	ds_read2_b64 v[222:225], v178 offset0:52 offset1:54
	ds_read2_b64 v[226:229], v250 offset0:84 offset1:86
	s_nop 0
	v_cvt_pk_bf16_f32 v230, v98, v99
	v_cvt_pk_bf16_f32 v231, v100, v101
	v_cvt_pk_bf16_f32 v232, v102, v103
	v_cvt_pk_bf16_f32 v233, v104, v105
	s_waitcnt lgkmcnt(2)
	s_nop 1
	v_mfma_f32_32x32x16_bf16 v[130:145], v[194:197], v[230:233], v[130:145]
	v_mfma_f32_32x32x16_bf16 v[234:249], v[218:221], v[230:233], v[234:249]
	ds_read2_b64 v[194:197], v178 offset0:56 offset1:58
	ds_read2_b64 v[218:221], v250 offset0:88 offset1:90
	s_nop 0
	v_cvt_pk_bf16_f32 v230, v106, v107
	v_cvt_pk_bf16_f32 v231, v108, v109
	v_cvt_pk_bf16_f32 v232, v110, v111
	v_cvt_pk_bf16_f32 v233, v112, v113
	s_waitcnt lgkmcnt(2)
	s_nop 1
	v_mfma_f32_32x32x16_bf16 v[130:145], v[222:225], v[230:233], v[130:145]
	v_mfma_f32_32x32x16_bf16 v[234:249], v[226:229], v[230:233], v[234:249]
	ds_read2_b64 v[222:225], v178 offset0:60 offset1:62
	ds_read2_b64 v[226:229], v250 offset0:92 offset1:94
	s_nop 0
	v_cvt_pk_bf16_f32 v230, v114, v115
	v_cvt_pk_bf16_f32 v231, v116, v117
	v_cvt_pk_bf16_f32 v232, v118, v119
	v_cvt_pk_bf16_f32 v233, v120, v121
	s_waitcnt lgkmcnt(2)
	s_nop 1
	v_mfma_f32_32x32x16_bf16 v[130:145], v[194:197], v[230:233], v[130:145]
	v_mfma_f32_32x32x16_bf16 v[234:249], v[218:221], v[230:233], v[234:249]
	s_nop 0
	v_cvt_pk_bf16_f32 v230, v122, v123
	v_cvt_pk_bf16_f32 v231, v124, v125
	v_cvt_pk_bf16_f32 v232, v126, v127
	v_cvt_pk_bf16_f32 v233, v128, v129
	s_waitcnt lgkmcnt(0)
	s_nop 1
	v_mfma_f32_32x32x16_bf16 v[130:145], v[222:225], v[230:233], v[130:145]
	v_mfma_f32_32x32x16_bf16 v[234:249], v[226:229], v[230:233], v[234:249]
	v_or_b32_e32 v172, v168, v174
	v_ashrrev_i32_e32 v173, 31, v172
	v_lshlrev_b64 v[172:173], 12, v[172:173]
	s_mov_b32 s100, 0xaaaaaaaa
	s_mov_b32 s101, 0xaaaaaaaa
	v_and_b32_e32 v220, 1, v189
	v_mul_u32_u24_e32 v220, 0xffe, v220
	v_mov_b32_e32 v221, 0
	v_lshl_add_u64 v[218:219], v[170:171], 0, v[172:173]
	v_lshl_add_u64 v[218:219], v[218:219], 0, v[220:221]
	s_mov_b32 s7, 0
	s_nop 7
	v_fma_f32 v222, 0, v192, v153
	v_add_f32_e32 v223, v153, v192
	v_exp_f32_e32 v222, v222
	v_exp_f32_e32 v223, v223
	s_nop 0
	v_mul_f32_e32 v222, v222, v130
	v_mul_f32_e32 v223, v223, v131
	s_nop 1
	v_mov_b32_dpp v224, v222 quad_perm:[1,0,3,2] row_mask:0xf bank_mask:0xf
	v_mov_b32_dpp v225, v223 quad_perm:[1,0,3,2] row_mask:0xf bank_mask:0xf
	v_cndmask_b32_e64 v226, v222, v225, s[100:101]
	v_cndmask_b32_e64 v227, v224, v223, s[100:101]
	v_cvt_pk_bf16_f32 v226, v226, v227
	s_mov_b32 s6, 0x0
	v_lshl_add_u64 v[228:229], v[218:219], 0, s[6:7]
	global_store_dword v[228:229], v226, off
	v_fma_f32 v222, 2.0, v192, v153
	v_fmamk_f32 v223, v192, 0x40400000, v153
	v_exp_f32_e32 v222, v222
	v_exp_f32_e32 v223, v223
	s_nop 0
	v_mul_f32_e32 v222, v222, v132
	v_mul_f32_e32 v223, v223, v133
	s_nop 1
	v_mov_b32_dpp v224, v222 quad_perm:[1,0,3,2] row_mask:0xf bank_mask:0xf
	v_mov_b32_dpp v225, v223 quad_perm:[1,0,3,2] row_mask:0xf bank_mask:0xf
	v_cndmask_b32_e64 v226, v222, v225, s[100:101]
	v_cndmask_b32_e64 v227, v224, v223, s[100:101]
	v_cvt_pk_bf16_f32 v226, v226, v227
	s_mov_b32 s6, 0x2000
	v_lshl_add_u64 v[228:229], v[218:219], 0, s[6:7]
	global_store_dword v[228:229], v226, off
	v_fmamk_f32 v222, v192, 0x41000000, v153
	v_fmamk_f32 v223, v192, 0x41100000, v153
	v_exp_f32_e32 v222, v222
	v_exp_f32_e32 v223, v223
	s_nop 0
	v_mul_f32_e32 v222, v222, v134
	v_mul_f32_e32 v223, v223, v135
	s_nop 1
	v_mov_b32_dpp v224, v222 quad_perm:[1,0,3,2] row_mask:0xf bank_mask:0xf
	v_mov_b32_dpp v225, v223 quad_perm:[1,0,3,2] row_mask:0xf bank_mask:0xf
	v_cndmask_b32_e64 v226, v222, v225, s[100:101]
	v_cndmask_b32_e64 v227, v224, v223, s[100:101]
	v_cvt_pk_bf16_f32 v226, v226, v227
	s_mov_b32 s6, 0x8000
	v_lshl_add_u64 v[228:229], v[218:219], 0, s[6:7]
	global_store_dword v[228:229], v226, off
	v_fmamk_f32 v222, v192, 0x41200000, v153
	v_fmamk_f32 v223, v192, 0x41300000, v153
	v_exp_f32_e32 v222, v222
	v_exp_f32_e32 v223, v223
	s_nop 0
	v_mul_f32_e32 v222, v222, v136
	v_mul_f32_e32 v223, v223, v137
	s_nop 1
	v_mov_b32_dpp v224, v222 quad_perm:[1,0,3,2] row_mask:0xf bank_mask:0xf
	v_mov_b32_dpp v225, v223 quad_perm:[1,0,3,2] row_mask:0xf bank_mask:0xf
	v_cndmask_b32_e64 v226, v222, v225, s[100:101]
	v_cndmask_b32_e64 v227, v224, v223, s[100:101]
	v_cvt_pk_bf16_f32 v226, v226, v227
	s_mov_b32 s6, 0xa000
	v_lshl_add_u64 v[228:229], v[218:219], 0, s[6:7]
	global_store_dword v[228:229], v226, off
	v_fmamk_f32 v222, v192, 0x41800000, v153
	v_fmamk_f32 v223, v192, 0x41880000, v153
	v_exp_f32_e32 v222, v222
	v_exp_f32_e32 v223, v223
	s_nop 0
	v_mul_f32_e32 v222, v222, v138
	v_mul_f32_e32 v223, v223, v139
	s_nop 1
	v_mov_b32_dpp v224, v222 quad_perm:[1,0,3,2] row_mask:0xf bank_mask:0xf
	v_mov_b32_dpp v225, v223 quad_perm:[1,0,3,2] row_mask:0xf bank_mask:0xf
	v_cndmask_b32_e64 v226, v222, v225, s[100:101]
	v_cndmask_b32_e64 v227, v224, v223, s[100:101]
	v_cvt_pk_bf16_f32 v226, v226, v227
	s_mov_b32 s6, 0x10000
	v_lshl_add_u64 v[228:229], v[218:219], 0, s[6:7]
	global_store_dword v[228:229], v226, off
	v_fmamk_f32 v222, v192, 0x41900000, v153
	v_fmamk_f32 v223, v192, 0x41980000, v153
	v_exp_f32_e32 v222, v222
	v_exp_f32_e32 v223, v223
	s_nop 0
	v_mul_f32_e32 v222, v222, v140
	v_mul_f32_e32 v223, v223, v141
	s_nop 1
	v_mov_b32_dpp v224, v222 quad_perm:[1,0,3,2] row_mask:0xf bank_mask:0xf
	v_mov_b32_dpp v225, v223 quad_perm:[1,0,3,2] row_mask:0xf bank_mask:0xf
	v_cndmask_b32_e64 v226, v222, v225, s[100:101]
	v_cndmask_b32_e64 v227, v224, v223, s[100:101]
	v_cvt_pk_bf16_f32 v226, v226, v227
	s_mov_b32 s6, 0x12000
	v_lshl_add_u64 v[228:229], v[218:219], 0, s[6:7]
	global_store_dword v[228:229], v226, off
	v_fmamk_f32 v222, v192, 0x41c00000, v153
	v_fmamk_f32 v223, v192, 0x41c80000, v153
	v_exp_f32_e32 v222, v222
	v_exp_f32_e32 v223, v223
	s_nop 0
	v_mul_f32_e32 v222, v222, v142
	v_mul_f32_e32 v223, v223, v143
	s_nop 1
	v_mov_b32_dpp v224, v222 quad_perm:[1,0,3,2] row_mask:0xf bank_mask:0xf
	v_mov_b32_dpp v225, v223 quad_perm:[1,0,3,2] row_mask:0xf bank_mask:0xf
	v_cndmask_b32_e64 v226, v222, v225, s[100:101]
	v_cndmask_b32_e64 v227, v224, v223, s[100:101]
	v_cvt_pk_bf16_f32 v226, v226, v227
	s_mov_b32 s6, 0x18000
	v_lshl_add_u64 v[228:229], v[218:219], 0, s[6:7]
	global_store_dword v[228:229], v226, off
	v_fmamk_f32 v222, v192, 0x41d00000, v153
	v_fmamk_f32 v223, v192, 0x41d80000, v153
	v_exp_f32_e32 v222, v222
	v_exp_f32_e32 v223, v223
	s_nop 0
	v_mul_f32_e32 v222, v222, v144
	v_mul_f32_e32 v223, v223, v145
	s_nop 1
	v_mov_b32_dpp v224, v222 quad_perm:[1,0,3,2] row_mask:0xf bank_mask:0xf
	v_mov_b32_dpp v225, v223 quad_perm:[1,0,3,2] row_mask:0xf bank_mask:0xf
	v_cndmask_b32_e64 v226, v222, v225, s[100:101]
	v_cndmask_b32_e64 v227, v224, v223, s[100:101]
	v_cvt_pk_bf16_f32 v226, v226, v227
	s_mov_b32 s6, 0x1a000
	v_lshl_add_u64 v[228:229], v[218:219], 0, s[6:7]
	global_store_dword v[228:229], v226, off
	v_mov_b32_e32 v130, v234
	v_mov_b32_e32 v131, v235
	v_mov_b32_e32 v132, v236
	v_mov_b32_e32 v133, v237
	v_mov_b32_e32 v134, v238
	v_mov_b32_e32 v135, v239
	v_mov_b32_e32 v136, v240
	v_mov_b32_e32 v137, v241
	v_mov_b32_e32 v138, v242
	v_mov_b32_e32 v139, v243
	v_mov_b32_e32 v140, v244
	v_mov_b32_e32 v141, v245
	v_mov_b32_e32 v142, v246
	v_mov_b32_e32 v143, v247
	v_mov_b32_e32 v144, v248
	v_mov_b32_e32 v145, v249
	s_mov_b32 s100, 0xaaaaaaaa
	s_mov_b32 s101, 0xaaaaaaaa
	v_and_b32_e32 v220, 1, v189
	v_mul_u32_u24_e32 v220, 0xffe, v220
	v_mov_b32_e32 v221, 0
	v_lshl_add_u64 v[218:219], v[170:171], 0, v[172:173]
	v_lshl_add_u64 v[218:219], v[218:219], 0, v[220:221]
	s_mov_b32 s7, 0
	s_nop 7
	v_fmamk_f32 v222, v192, 0x42000000, v153
	v_fmamk_f32 v223, v192, 0x42040000, v153
	v_exp_f32_e32 v222, v222
	v_exp_f32_e32 v223, v223
	s_nop 0
	v_mul_f32_e32 v222, v222, v130
	v_mul_f32_e32 v223, v223, v131
	s_nop 1
	v_mov_b32_dpp v224, v222 quad_perm:[1,0,3,2] row_mask:0xf bank_mask:0xf
	v_mov_b32_dpp v225, v223 quad_perm:[1,0,3,2] row_mask:0xf bank_mask:0xf
	v_cndmask_b32_e64 v226, v222, v225, s[100:101]
	v_cndmask_b32_e64 v227, v224, v223, s[100:101]
	v_cvt_pk_bf16_f32 v226, v226, v227
	s_mov_b32 s6, 0x20000
	v_lshl_add_u64 v[228:229], v[218:219], 0, s[6:7]
	global_store_dword v[228:229], v226, off
	v_fmamk_f32 v222, v192, 0x42080000, v153
	v_fmamk_f32 v223, v192, 0x420c0000, v153
	v_exp_f32_e32 v222, v222
	v_exp_f32_e32 v223, v223
	s_nop 0
	v_mul_f32_e32 v222, v222, v132
	v_mul_f32_e32 v223, v223, v133
	s_nop 1
	v_mov_b32_dpp v224, v222 quad_perm:[1,0,3,2] row_mask:0xf bank_mask:0xf
	v_mov_b32_dpp v225, v223 quad_perm:[1,0,3,2] row_mask:0xf bank_mask:0xf
	v_cndmask_b32_e64 v226, v222, v225, s[100:101]
	v_cndmask_b32_e64 v227, v224, v223, s[100:101]
	v_cvt_pk_bf16_f32 v226, v226, v227
	s_mov_b32 s6, 0x22000
	v_lshl_add_u64 v[228:229], v[218:219], 0, s[6:7]
	global_store_dword v[228:229], v226, off
	v_fmamk_f32 v222, v192, 0x42200000, v153
	v_fmamk_f32 v223, v192, 0x42240000, v153
	v_exp_f32_e32 v222, v222
	v_exp_f32_e32 v223, v223
	s_nop 0
	v_mul_f32_e32 v222, v222, v134
	v_mul_f32_e32 v223, v223, v135
	s_nop 1
	v_mov_b32_dpp v224, v222 quad_perm:[1,0,3,2] row_mask:0xf bank_mask:0xf
	v_mov_b32_dpp v225, v223 quad_perm:[1,0,3,2] row_mask:0xf bank_mask:0xf
	v_cndmask_b32_e64 v226, v222, v225, s[100:101]
	v_cndmask_b32_e64 v227, v224, v223, s[100:101]
	v_cvt_pk_bf16_f32 v226, v226, v227
	s_mov_b32 s6, 0x28000
	v_lshl_add_u64 v[228:229], v[218:219], 0, s[6:7]
	global_store_dword v[228:229], v226, off
	v_fmamk_f32 v222, v192, 0x42280000, v153
	v_fmamk_f32 v223, v192, 0x422c0000, v153
	v_exp_f32_e32 v222, v222
	v_exp_f32_e32 v223, v223
	s_nop 0
	v_mul_f32_e32 v222, v222, v136
	v_mul_f32_e32 v223, v223, v137
	s_nop 1
	v_mov_b32_dpp v224, v222 quad_perm:[1,0,3,2] row_mask:0xf bank_mask:0xf
	v_mov_b32_dpp v225, v223 quad_perm:[1,0,3,2] row_mask:0xf bank_mask:0xf
	v_cndmask_b32_e64 v226, v222, v225, s[100:101]
	v_cndmask_b32_e64 v227, v224, v223, s[100:101]
	v_cvt_pk_bf16_f32 v226, v226, v227
	s_mov_b32 s6, 0x2a000
	v_lshl_add_u64 v[228:229], v[218:219], 0, s[6:7]
	global_store_dword v[228:229], v226, off
	v_fmamk_f32 v222, v192, 0x42400000, v153
	v_fmamk_f32 v223, v192, 0x42440000, v153
	v_exp_f32_e32 v222, v222
	v_exp_f32_e32 v223, v223
	s_nop 0
	v_mul_f32_e32 v222, v222, v138
	v_mul_f32_e32 v223, v223, v139
	s_nop 1
	v_mov_b32_dpp v224, v222 quad_perm:[1,0,3,2] row_mask:0xf bank_mask:0xf
	v_mov_b32_dpp v225, v223 quad_perm:[1,0,3,2] row_mask:0xf bank_mask:0xf
	v_cndmask_b32_e64 v226, v222, v225, s[100:101]
	v_cndmask_b32_e64 v227, v224, v223, s[100:101]
	v_cvt_pk_bf16_f32 v226, v226, v227
	s_mov_b32 s6, 0x30000
	v_lshl_add_u64 v[228:229], v[218:219], 0, s[6:7]
	global_store_dword v[228:229], v226, off
	v_fmamk_f32 v222, v192, 0x42480000, v153
	v_fmamk_f32 v223, v192, 0x424c0000, v153
	v_exp_f32_e32 v222, v222
	v_exp_f32_e32 v223, v223
	s_nop 0
	v_mul_f32_e32 v222, v222, v140
	v_mul_f32_e32 v223, v223, v141
	s_nop 1
	v_mov_b32_dpp v224, v222 quad_perm:[1,0,3,2] row_mask:0xf bank_mask:0xf
	v_mov_b32_dpp v225, v223 quad_perm:[1,0,3,2] row_mask:0xf bank_mask:0xf
	v_cndmask_b32_e64 v226, v222, v225, s[100:101]
	v_cndmask_b32_e64 v227, v224, v223, s[100:101]
	v_cvt_pk_bf16_f32 v226, v226, v227
	s_mov_b32 s6, 0x32000
	v_lshl_add_u64 v[228:229], v[218:219], 0, s[6:7]
	global_store_dword v[228:229], v226, off
	v_fmamk_f32 v222, v192, 0x42600000, v153
	v_fmamk_f32 v223, v192, 0x42640000, v153
	v_exp_f32_e32 v222, v222
	v_exp_f32_e32 v223, v223
	s_nop 0
	v_mul_f32_e32 v222, v222, v142
	v_mul_f32_e32 v223, v223, v143
	s_nop 1
	v_mov_b32_dpp v224, v222 quad_perm:[1,0,3,2] row_mask:0xf bank_mask:0xf
	v_mov_b32_dpp v225, v223 quad_perm:[1,0,3,2] row_mask:0xf bank_mask:0xf
	v_cndmask_b32_e64 v226, v222, v225, s[100:101]
	v_cndmask_b32_e64 v227, v224, v223, s[100:101]
	v_cvt_pk_bf16_f32 v226, v226, v227
	s_mov_b32 s6, 0x38000
	v_lshl_add_u64 v[228:229], v[218:219], 0, s[6:7]
	global_store_dword v[228:229], v226, off
	v_fmamk_f32 v222, v192, 0x42680000, v153
	v_fmamk_f32 v223, v192, 0x426c0000, v153
	v_exp_f32_e32 v222, v222
	v_exp_f32_e32 v223, v223
	s_nop 0
	v_mul_f32_e32 v222, v222, v144
	v_mul_f32_e32 v223, v223, v145
	s_nop 1
	v_mov_b32_dpp v224, v222 quad_perm:[1,0,3,2] row_mask:0xf bank_mask:0xf
	v_mov_b32_dpp v225, v223 quad_perm:[1,0,3,2] row_mask:0xf bank_mask:0xf
	v_cndmask_b32_e64 v226, v222, v225, s[100:101]
	v_cndmask_b32_e64 v227, v224, v223, s[100:101]
	v_cvt_pk_bf16_f32 v226, v226, v227
	s_mov_b32 s6, 0x3a000
	v_lshl_add_u64 v[228:229], v[218:219], 0, s[6:7]
	global_store_dword v[228:229], v226, off
	v_add_u32_e32 v250, 0xc000, v178
	v_add_u32_e32 v251, 0x8000, v178
	ds_read2_b64 v[194:197], v251 offset0:64 offset1:66
	ds_read2_b64 v[218:221], v250 offset0:96 offset1:98
	ds_read2_b64 v[222:225], v251 offset0:68 offset1:70
	ds_read2_b64 v[226:229], v250 offset0:100 offset1:102
	s_nop 0
	v_cvt_pk_bf16_f32 v230, v2, v3
	v_cvt_pk_bf16_f32 v231, v4, v5
	v_cvt_pk_bf16_f32 v232, v6, v7
	v_cvt_pk_bf16_f32 v233, v8, v9
	s_waitcnt lgkmcnt(2)
	s_nop 1
	v_mfma_f32_32x32x16_bf16 v[130:145], v[194:197], v[230:233], 0
	v_mfma_f32_32x32x16_bf16 v[234:249], v[218:221], v[230:233], 0
	ds_read2_b64 v[194:197], v251 offset0:72 offset1:74
	ds_read2_b64 v[218:221], v250 offset0:104 offset1:106
	s_nop 0
	v_cvt_pk_bf16_f32 v230, v10, v11
	v_cvt_pk_bf16_f32 v231, v12, v13
	v_cvt_pk_bf16_f32 v232, v14, v15
	v_cvt_pk_bf16_f32 v233, v16, v17
	s_waitcnt lgkmcnt(2)
	s_nop 1
	v_mfma_f32_32x32x16_bf16 v[130:145], v[222:225], v[230:233], v[130:145]
	v_mfma_f32_32x32x16_bf16 v[234:249], v[226:229], v[230:233], v[234:249]
	ds_read2_b64 v[222:225], v251 offset0:76 offset1:78
	ds_read2_b64 v[226:229], v250 offset0:108 offset1:110
	s_nop 0
	v_cvt_pk_bf16_f32 v230, v18, v19
	v_cvt_pk_bf16_f32 v231, v20, v21
	v_cvt_pk_bf16_f32 v232, v22, v23
	v_cvt_pk_bf16_f32 v233, v24, v25
	s_waitcnt lgkmcnt(2)
	s_nop 1
	v_mfma_f32_32x32x16_bf16 v[130:145], v[194:197], v[230:233], v[130:145]
	v_mfma_f32_32x32x16_bf16 v[234:249], v[218:221], v[230:233], v[234:249]
	ds_read2_b64 v[194:197], v251 offset0:80 offset1:82
	ds_read2_b64 v[218:221], v250 offset0:112 offset1:114
	s_nop 0
	v_cvt_pk_bf16_f32 v230, v26, v27
	v_cvt_pk_bf16_f32 v231, v28, v29
	v_cvt_pk_bf16_f32 v232, v30, v31
	v_cvt_pk_bf16_f32 v233, v32, v33
	s_waitcnt lgkmcnt(2)
	s_nop 1
	v_mfma_f32_32x32x16_bf16 v[130:145], v[222:225], v[230:233], v[130:145]
	v_mfma_f32_32x32x16_bf16 v[234:249], v[226:229], v[230:233], v[234:249]
	ds_read2_b64 v[222:225], v251 offset0:84 offset1:86
	ds_read2_b64 v[226:229], v250 offset0:116 offset1:118
	s_nop 0
	v_cvt_pk_bf16_f32 v230, v34, v35
	v_cvt_pk_bf16_f32 v231, v36, v37
	v_cvt_pk_bf16_f32 v232, v38, v39
	v_cvt_pk_bf16_f32 v233, v40, v41
	s_waitcnt lgkmcnt(2)
	s_nop 1
	v_mfma_f32_32x32x16_bf16 v[130:145], v[194:197], v[230:233], v[130:145]
	v_mfma_f32_32x32x16_bf16 v[234:249], v[218:221], v[230:233], v[234:249]
	ds_read2_b64 v[194:197], v251 offset0:88 offset1:90
	ds_read2_b64 v[218:221], v250 offset0:120 offset1:122
	s_nop 0
	v_cvt_pk_bf16_f32 v230, v42, v43
	v_cvt_pk_bf16_f32 v231, v44, v45
	v_cvt_pk_bf16_f32 v232, v46, v47
	v_cvt_pk_bf16_f32 v233, v48, v49
	s_waitcnt lgkmcnt(2)
	s_nop 1
	v_mfma_f32_32x32x16_bf16 v[130:145], v[222:225], v[230:233], v[130:145]
	v_mfma_f32_32x32x16_bf16 v[234:249], v[226:229], v[230:233], v[234:249]
	ds_read2_b64 v[222:225], v251 offset0:92 offset1:94
	ds_read2_b64 v[226:229], v250 offset0:124 offset1:126
	s_nop 0
	v_cvt_pk_bf16_f32 v230, v50, v51
	v_cvt_pk_bf16_f32 v231, v52, v53
	v_cvt_pk_bf16_f32 v232, v54, v55
	v_cvt_pk_bf16_f32 v233, v56, v57
	s_waitcnt lgkmcnt(2)
	s_nop 1
	v_mfma_f32_32x32x16_bf16 v[130:145], v[194:197], v[230:233], v[130:145]
	v_mfma_f32_32x32x16_bf16 v[234:249], v[218:221], v[230:233], v[234:249]
	ds_read2_b64 v[194:197], v251 offset0:96 offset1:98
	ds_read2_b64 v[218:221], v250 offset0:128 offset1:130
	s_nop 0
	v_cvt_pk_bf16_f32 v230, v58, v59
	v_cvt_pk_bf16_f32 v231, v60, v61
	v_cvt_pk_bf16_f32 v232, v62, v63
	v_cvt_pk_bf16_f32 v233, v64, v65
	s_waitcnt lgkmcnt(2)
	s_nop 1
	v_mfma_f32_32x32x16_bf16 v[130:145], v[222:225], v[230:233], v[130:145]
	v_mfma_f32_32x32x16_bf16 v[234:249], v[226:229], v[230:233], v[234:249]
	ds_read2_b64 v[222:225], v251 offset0:100 offset1:102
	ds_read2_b64 v[226:229], v250 offset0:132 offset1:134
	s_nop 0
	v_cvt_pk_bf16_f32 v230, v66, v67
	v_cvt_pk_bf16_f32 v231, v68, v69
	v_cvt_pk_bf16_f32 v232, v70, v71
	v_cvt_pk_bf16_f32 v233, v72, v73
	s_waitcnt lgkmcnt(2)
	s_nop 1
	v_mfma_f32_32x32x16_bf16 v[130:145], v[194:197], v[230:233], v[130:145]
	v_mfma_f32_32x32x16_bf16 v[234:249], v[218:221], v[230:233], v[234:249]
	ds_read2_b64 v[194:197], v251 offset0:104 offset1:106
	ds_read2_b64 v[218:221], v250 offset0:136 offset1:138
	s_nop 0
	v_cvt_pk_bf16_f32 v230, v74, v75
	v_cvt_pk_bf16_f32 v231, v76, v77
	v_cvt_pk_bf16_f32 v232, v78, v79
	v_cvt_pk_bf16_f32 v233, v80, v81
	s_waitcnt lgkmcnt(2)
	s_nop 1
	v_mfma_f32_32x32x16_bf16 v[130:145], v[222:225], v[230:233], v[130:145]
	v_mfma_f32_32x32x16_bf16 v[234:249], v[226:229], v[230:233], v[234:249]
	ds_read2_b64 v[222:225], v251 offset0:108 offset1:110
	ds_read2_b64 v[226:229], v250 offset0:140 offset1:142
	s_nop 0
	v_cvt_pk_bf16_f32 v230, v82, v83
	v_cvt_pk_bf16_f32 v231, v84, v85
	v_cvt_pk_bf16_f32 v232, v86, v87
	v_cvt_pk_bf16_f32 v233, v88, v89
	s_waitcnt lgkmcnt(2)
	s_nop 1
	v_mfma_f32_32x32x16_bf16 v[130:145], v[194:197], v[230:233], v[130:145]
	v_mfma_f32_32x32x16_bf16 v[234:249], v[218:221], v[230:233], v[234:249]
	ds_read2_b64 v[194:197], v251 offset0:112 offset1:114
	ds_read2_b64 v[218:221], v250 offset0:144 offset1:146
	s_nop 0
	v_cvt_pk_bf16_f32 v230, v90, v91
	v_cvt_pk_bf16_f32 v231, v92, v93
	v_cvt_pk_bf16_f32 v232, v94, v95
	v_cvt_pk_bf16_f32 v233, v96, v97
	s_waitcnt lgkmcnt(2)
	s_nop 1
	v_mfma_f32_32x32x16_bf16 v[130:145], v[222:225], v[230:233], v[130:145]
	v_mfma_f32_32x32x16_bf16 v[234:249], v[226:229], v[230:233], v[234:249]
	ds_read2_b64 v[222:225], v251 offset0:116 offset1:118
	ds_read2_b64 v[226:229], v250 offset0:148 offset1:150
	s_nop 0
	v_cvt_pk_bf16_f32 v230, v98, v99
	v_cvt_pk_bf16_f32 v231, v100, v101
	v_cvt_pk_bf16_f32 v232, v102, v103
	v_cvt_pk_bf16_f32 v233, v104, v105
	s_waitcnt lgkmcnt(2)
	s_nop 1
	v_mfma_f32_32x32x16_bf16 v[130:145], v[194:197], v[230:233], v[130:145]
	v_mfma_f32_32x32x16_bf16 v[234:249], v[218:221], v[230:233], v[234:249]
	ds_read2_b64 v[194:197], v251 offset0:120 offset1:122
	ds_read2_b64 v[218:221], v250 offset0:152 offset1:154
	s_nop 0
	v_cvt_pk_bf16_f32 v230, v106, v107
	v_cvt_pk_bf16_f32 v231, v108, v109
	v_cvt_pk_bf16_f32 v232, v110, v111
	v_cvt_pk_bf16_f32 v233, v112, v113
	s_waitcnt lgkmcnt(2)
	s_nop 1
	v_mfma_f32_32x32x16_bf16 v[130:145], v[222:225], v[230:233], v[130:145]
	v_mfma_f32_32x32x16_bf16 v[234:249], v[226:229], v[230:233], v[234:249]
	ds_read2_b64 v[222:225], v251 offset0:124 offset1:126
	ds_read2_b64 v[226:229], v250 offset0:156 offset1:158
	s_nop 0
	v_cvt_pk_bf16_f32 v230, v114, v115
	v_cvt_pk_bf16_f32 v231, v116, v117
	v_cvt_pk_bf16_f32 v232, v118, v119
	v_cvt_pk_bf16_f32 v233, v120, v121
	s_waitcnt lgkmcnt(2)
	s_nop 1
	v_mfma_f32_32x32x16_bf16 v[130:145], v[194:197], v[230:233], v[130:145]
	v_mfma_f32_32x32x16_bf16 v[234:249], v[218:221], v[230:233], v[234:249]
	s_nop 0
	v_cvt_pk_bf16_f32 v230, v122, v123
	v_cvt_pk_bf16_f32 v231, v124, v125
	v_cvt_pk_bf16_f32 v232, v126, v127
	v_cvt_pk_bf16_f32 v233, v128, v129
	s_waitcnt lgkmcnt(0)
	s_nop 1
	v_mfma_f32_32x32x16_bf16 v[130:145], v[222:225], v[230:233], v[130:145]
	v_mfma_f32_32x32x16_bf16 v[234:249], v[226:229], v[230:233], v[234:249]
	s_mov_b32 s100, 0xaaaaaaaa
	s_mov_b32 s101, 0xaaaaaaaa
	v_and_b32_e32 v220, 1, v189
	v_mul_u32_u24_e32 v220, 0xffe, v220
	v_mov_b32_e32 v221, 0
	v_lshl_add_u64 v[218:219], v[170:171], 0, v[172:173]
	v_lshl_add_u64 v[218:219], v[218:219], 0, v[220:221]
	s_mov_b32 s7, 0
	s_nop 7
	v_fmamk_f32 v222, v192, 0x42800000, v153
	v_fmamk_f32 v223, v192, 0x42820000, v153
	v_exp_f32_e32 v222, v222
	v_exp_f32_e32 v223, v223
	s_nop 0
	v_mul_f32_e32 v222, v222, v130
	v_mul_f32_e32 v223, v223, v131
	s_nop 1
	v_mov_b32_dpp v224, v222 quad_perm:[1,0,3,2] row_mask:0xf bank_mask:0xf
	v_mov_b32_dpp v225, v223 quad_perm:[1,0,3,2] row_mask:0xf bank_mask:0xf
	v_cndmask_b32_e64 v226, v222, v225, s[100:101]
	v_cndmask_b32_e64 v227, v224, v223, s[100:101]
	v_cvt_pk_bf16_f32 v226, v226, v227
	s_mov_b32 s6, 0x40000
	v_lshl_add_u64 v[228:229], v[218:219], 0, s[6:7]
	global_store_dword v[228:229], v226, off
	v_fmamk_f32 v222, v192, 0x42840000, v153
	v_fmamk_f32 v223, v192, 0x42860000, v153
	v_exp_f32_e32 v222, v222
	v_exp_f32_e32 v223, v223
	s_nop 0
	v_mul_f32_e32 v222, v222, v132
	v_mul_f32_e32 v223, v223, v133
	s_nop 1
	v_mov_b32_dpp v224, v222 quad_perm:[1,0,3,2] row_mask:0xf bank_mask:0xf
	v_mov_b32_dpp v225, v223 quad_perm:[1,0,3,2] row_mask:0xf bank_mask:0xf
	v_cndmask_b32_e64 v226, v222, v225, s[100:101]
	v_cndmask_b32_e64 v227, v224, v223, s[100:101]
	v_cvt_pk_bf16_f32 v226, v226, v227
	s_mov_b32 s6, 0x42000
	v_lshl_add_u64 v[228:229], v[218:219], 0, s[6:7]
	global_store_dword v[228:229], v226, off
	v_fmamk_f32 v222, v192, 0x42900000, v153
	v_fmamk_f32 v223, v192, 0x42920000, v153
	v_exp_f32_e32 v222, v222
	v_exp_f32_e32 v223, v223
	s_nop 0
	v_mul_f32_e32 v222, v222, v134
	v_mul_f32_e32 v223, v223, v135
	s_nop 1
	v_mov_b32_dpp v224, v222 quad_perm:[1,0,3,2] row_mask:0xf bank_mask:0xf
	v_mov_b32_dpp v225, v223 quad_perm:[1,0,3,2] row_mask:0xf bank_mask:0xf
	v_cndmask_b32_e64 v226, v222, v225, s[100:101]
	v_cndmask_b32_e64 v227, v224, v223, s[100:101]
	v_cvt_pk_bf16_f32 v226, v226, v227
	s_mov_b32 s6, 0x48000
	v_lshl_add_u64 v[228:229], v[218:219], 0, s[6:7]
	global_store_dword v[228:229], v226, off
	v_fmamk_f32 v222, v192, 0x42940000, v153
	v_fmamk_f32 v223, v192, 0x42960000, v153
	v_exp_f32_e32 v222, v222
	v_exp_f32_e32 v223, v223
	s_nop 0
	v_mul_f32_e32 v222, v222, v136
	v_mul_f32_e32 v223, v223, v137
	s_nop 1
	v_mov_b32_dpp v224, v222 quad_perm:[1,0,3,2] row_mask:0xf bank_mask:0xf
	v_mov_b32_dpp v225, v223 quad_perm:[1,0,3,2] row_mask:0xf bank_mask:0xf
	v_cndmask_b32_e64 v226, v222, v225, s[100:101]
	v_cndmask_b32_e64 v227, v224, v223, s[100:101]
	v_cvt_pk_bf16_f32 v226, v226, v227
	s_mov_b32 s6, 0x4a000
	v_lshl_add_u64 v[228:229], v[218:219], 0, s[6:7]
	global_store_dword v[228:229], v226, off
	v_fmamk_f32 v222, v192, 0x42a00000, v153
	v_fmamk_f32 v223, v192, 0x42a20000, v153
	v_exp_f32_e32 v222, v222
	v_exp_f32_e32 v223, v223
	s_nop 0
	v_mul_f32_e32 v222, v222, v138
	v_mul_f32_e32 v223, v223, v139
	s_nop 1
	v_mov_b32_dpp v224, v222 quad_perm:[1,0,3,2] row_mask:0xf bank_mask:0xf
	v_mov_b32_dpp v225, v223 quad_perm:[1,0,3,2] row_mask:0xf bank_mask:0xf
	v_cndmask_b32_e64 v226, v222, v225, s[100:101]
	v_cndmask_b32_e64 v227, v224, v223, s[100:101]
	v_cvt_pk_bf16_f32 v226, v226, v227
	s_mov_b32 s6, 0x50000
	v_lshl_add_u64 v[228:229], v[218:219], 0, s[6:7]
	global_store_dword v[228:229], v226, off
	v_fmamk_f32 v222, v192, 0x42a40000, v153
	v_fmamk_f32 v223, v192, 0x42a60000, v153
	v_exp_f32_e32 v222, v222
	v_exp_f32_e32 v223, v223
	s_nop 0
	v_mul_f32_e32 v222, v222, v140
	v_mul_f32_e32 v223, v223, v141
	s_nop 1
	v_mov_b32_dpp v224, v222 quad_perm:[1,0,3,2] row_mask:0xf bank_mask:0xf
	v_mov_b32_dpp v225, v223 quad_perm:[1,0,3,2] row_mask:0xf bank_mask:0xf
	v_cndmask_b32_e64 v226, v222, v225, s[100:101]
	v_cndmask_b32_e64 v227, v224, v223, s[100:101]
	v_cvt_pk_bf16_f32 v226, v226, v227
	s_mov_b32 s6, 0x52000
	v_lshl_add_u64 v[228:229], v[218:219], 0, s[6:7]
	global_store_dword v[228:229], v226, off
	v_fmamk_f32 v222, v192, 0x42b00000, v153
	v_fmamk_f32 v223, v192, 0x42b20000, v153
	v_exp_f32_e32 v222, v222
	v_exp_f32_e32 v223, v223
	s_nop 0
	v_mul_f32_e32 v222, v222, v142
	v_mul_f32_e32 v223, v223, v143
	s_nop 1
	v_mov_b32_dpp v224, v222 quad_perm:[1,0,3,2] row_mask:0xf bank_mask:0xf
	v_mov_b32_dpp v225, v223 quad_perm:[1,0,3,2] row_mask:0xf bank_mask:0xf
	v_cndmask_b32_e64 v226, v222, v225, s[100:101]
	v_cndmask_b32_e64 v227, v224, v223, s[100:101]
	v_cvt_pk_bf16_f32 v226, v226, v227
	s_mov_b32 s6, 0x58000
	v_lshl_add_u64 v[228:229], v[218:219], 0, s[6:7]
	global_store_dword v[228:229], v226, off
	v_fmamk_f32 v222, v192, 0x42b40000, v153
	v_fmamk_f32 v223, v192, 0x42b60000, v153
	v_exp_f32_e32 v222, v222
	v_exp_f32_e32 v223, v223
	s_nop 0
	v_mul_f32_e32 v222, v222, v144
	v_mul_f32_e32 v223, v223, v145
	s_nop 1
	v_mov_b32_dpp v224, v222 quad_perm:[1,0,3,2] row_mask:0xf bank_mask:0xf
	v_mov_b32_dpp v225, v223 quad_perm:[1,0,3,2] row_mask:0xf bank_mask:0xf
	v_cndmask_b32_e64 v226, v222, v225, s[100:101]
	v_cndmask_b32_e64 v227, v224, v223, s[100:101]
	v_cvt_pk_bf16_f32 v226, v226, v227
	s_mov_b32 s6, 0x5a000
	v_lshl_add_u64 v[228:229], v[218:219], 0, s[6:7]
	global_store_dword v[228:229], v226, off
	v_mov_b32_e32 v130, v234
	v_mov_b32_e32 v131, v235
	v_mov_b32_e32 v132, v236
	v_mov_b32_e32 v133, v237
	v_mov_b32_e32 v134, v238
	v_mov_b32_e32 v135, v239
	v_mov_b32_e32 v136, v240
	v_mov_b32_e32 v137, v241
	v_mov_b32_e32 v138, v242
	v_mov_b32_e32 v139, v243
	v_mov_b32_e32 v140, v244
	v_mov_b32_e32 v141, v245
	v_mov_b32_e32 v142, v246
	v_mov_b32_e32 v143, v247
	v_mov_b32_e32 v144, v248
	v_mov_b32_e32 v145, v249
	s_mov_b32 s100, 0xaaaaaaaa
	s_mov_b32 s101, 0xaaaaaaaa
	v_and_b32_e32 v220, 1, v189
	v_mul_u32_u24_e32 v220, 0xffe, v220
	v_mov_b32_e32 v221, 0
	v_lshl_add_u64 v[218:219], v[170:171], 0, v[172:173]
	v_lshl_add_u64 v[218:219], v[218:219], 0, v[220:221]
	s_mov_b32 s7, 0
	s_nop 7
	v_fmamk_f32 v222, v192, 0x42c00000, v153
	v_fmamk_f32 v223, v192, 0x42c20000, v153
	v_exp_f32_e32 v222, v222
	v_exp_f32_e32 v223, v223
	s_nop 0
	v_mul_f32_e32 v222, v222, v130
	v_mul_f32_e32 v223, v223, v131
	s_nop 1
	v_mov_b32_dpp v224, v222 quad_perm:[1,0,3,2] row_mask:0xf bank_mask:0xf
	v_mov_b32_dpp v225, v223 quad_perm:[1,0,3,2] row_mask:0xf bank_mask:0xf
	v_cndmask_b32_e64 v226, v222, v225, s[100:101]
	v_cndmask_b32_e64 v227, v224, v223, s[100:101]
	v_cvt_pk_bf16_f32 v226, v226, v227
	s_mov_b32 s6, 0x60000
	v_lshl_add_u64 v[228:229], v[218:219], 0, s[6:7]
	global_store_dword v[228:229], v226, off
	v_fmamk_f32 v222, v192, 0x42c40000, v153
	v_fmamk_f32 v223, v192, 0x42c60000, v153
	v_exp_f32_e32 v222, v222
	v_exp_f32_e32 v223, v223
	s_nop 0
	v_mul_f32_e32 v222, v222, v132
	v_mul_f32_e32 v223, v223, v133
	s_nop 1
	v_mov_b32_dpp v224, v222 quad_perm:[1,0,3,2] row_mask:0xf bank_mask:0xf
	v_mov_b32_dpp v225, v223 quad_perm:[1,0,3,2] row_mask:0xf bank_mask:0xf
	v_cndmask_b32_e64 v226, v222, v225, s[100:101]
	v_cndmask_b32_e64 v227, v224, v223, s[100:101]
	v_cvt_pk_bf16_f32 v226, v226, v227
	s_mov_b32 s6, 0x62000
	v_lshl_add_u64 v[228:229], v[218:219], 0, s[6:7]
	global_store_dword v[228:229], v226, off
	v_fmamk_f32 v222, v192, 0x42d00000, v153
	v_fmamk_f32 v223, v192, 0x42d20000, v153
	v_exp_f32_e32 v222, v222
	v_exp_f32_e32 v223, v223
	s_nop 0
	v_mul_f32_e32 v222, v222, v134
	v_mul_f32_e32 v223, v223, v135
	s_nop 1
	v_mov_b32_dpp v224, v222 quad_perm:[1,0,3,2] row_mask:0xf bank_mask:0xf
	v_mov_b32_dpp v225, v223 quad_perm:[1,0,3,2] row_mask:0xf bank_mask:0xf
	v_cndmask_b32_e64 v226, v222, v225, s[100:101]
	v_cndmask_b32_e64 v227, v224, v223, s[100:101]
	v_cvt_pk_bf16_f32 v226, v226, v227
	s_mov_b32 s6, 0x68000
	v_lshl_add_u64 v[228:229], v[218:219], 0, s[6:7]
	global_store_dword v[228:229], v226, off
	v_fmamk_f32 v222, v192, 0x42d40000, v153
	v_fmamk_f32 v223, v192, 0x42d60000, v153
	v_exp_f32_e32 v222, v222
	v_exp_f32_e32 v223, v223
	s_nop 0
	v_mul_f32_e32 v222, v222, v136
	v_mul_f32_e32 v223, v223, v137
	s_nop 1
	v_mov_b32_dpp v224, v222 quad_perm:[1,0,3,2] row_mask:0xf bank_mask:0xf
	v_mov_b32_dpp v225, v223 quad_perm:[1,0,3,2] row_mask:0xf bank_mask:0xf
	v_cndmask_b32_e64 v226, v222, v225, s[100:101]
	v_cndmask_b32_e64 v227, v224, v223, s[100:101]
	v_cvt_pk_bf16_f32 v226, v226, v227
	s_mov_b32 s6, 0x6a000
	v_lshl_add_u64 v[228:229], v[218:219], 0, s[6:7]
	global_store_dword v[228:229], v226, off
	v_fmamk_f32 v222, v192, 0x42e00000, v153
	v_fmamk_f32 v223, v192, 0x42e20000, v153
	v_exp_f32_e32 v222, v222
	v_exp_f32_e32 v223, v223
	s_nop 0
	v_mul_f32_e32 v222, v222, v138
	v_mul_f32_e32 v223, v223, v139
	s_nop 1
	v_mov_b32_dpp v224, v222 quad_perm:[1,0,3,2] row_mask:0xf bank_mask:0xf
	v_mov_b32_dpp v225, v223 quad_perm:[1,0,3,2] row_mask:0xf bank_mask:0xf
	v_cndmask_b32_e64 v226, v222, v225, s[100:101]
	v_cndmask_b32_e64 v227, v224, v223, s[100:101]
	v_cvt_pk_bf16_f32 v226, v226, v227
	s_mov_b32 s6, 0x70000
	v_lshl_add_u64 v[228:229], v[218:219], 0, s[6:7]
	global_store_dword v[228:229], v226, off
	v_fmamk_f32 v222, v192, 0x42e40000, v153
	v_fmamk_f32 v223, v192, 0x42e60000, v153
	v_exp_f32_e32 v222, v222
	v_exp_f32_e32 v223, v223
	s_nop 0
	v_mul_f32_e32 v222, v222, v140
	v_mul_f32_e32 v223, v223, v141
	s_nop 1
	v_mov_b32_dpp v224, v222 quad_perm:[1,0,3,2] row_mask:0xf bank_mask:0xf
	v_mov_b32_dpp v225, v223 quad_perm:[1,0,3,2] row_mask:0xf bank_mask:0xf
	v_cndmask_b32_e64 v226, v222, v225, s[100:101]
	v_cndmask_b32_e64 v227, v224, v223, s[100:101]
	v_cvt_pk_bf16_f32 v226, v226, v227
	s_mov_b32 s6, 0x72000
	v_lshl_add_u64 v[228:229], v[218:219], 0, s[6:7]
	global_store_dword v[228:229], v226, off
	v_fmamk_f32 v222, v192, 0x42f00000, v153
	v_fmamk_f32 v223, v192, 0x42f20000, v153
	v_exp_f32_e32 v222, v222
	v_exp_f32_e32 v223, v223
	s_nop 0
	v_mul_f32_e32 v222, v222, v142
	v_mul_f32_e32 v223, v223, v143
	s_nop 1
	v_mov_b32_dpp v224, v222 quad_perm:[1,0,3,2] row_mask:0xf bank_mask:0xf
	v_mov_b32_dpp v225, v223 quad_perm:[1,0,3,2] row_mask:0xf bank_mask:0xf
	v_cndmask_b32_e64 v226, v222, v225, s[100:101]
	v_cndmask_b32_e64 v227, v224, v223, s[100:101]
	v_cvt_pk_bf16_f32 v226, v226, v227
	s_mov_b32 s6, 0x78000
	v_lshl_add_u64 v[228:229], v[218:219], 0, s[6:7]
	global_store_dword v[228:229], v226, off
	v_fmamk_f32 v222, v192, 0x42f40000, v153
	v_fmamk_f32 v223, v192, 0x42f60000, v153
	v_exp_f32_e32 v222, v222
	v_exp_f32_e32 v223, v223
	s_nop 0
	v_mul_f32_e32 v222, v222, v144
	v_mul_f32_e32 v223, v223, v145
	s_nop 1
	v_mov_b32_dpp v224, v222 quad_perm:[1,0,3,2] row_mask:0xf bank_mask:0xf
	v_mov_b32_dpp v225, v223 quad_perm:[1,0,3,2] row_mask:0xf bank_mask:0xf
	v_cndmask_b32_e64 v226, v222, v225, s[100:101]
	v_cndmask_b32_e64 v227, v224, v223, s[100:101]
	v_cvt_pk_bf16_f32 v226, v226, v227
	s_mov_b32 s6, 0x7a000
	v_lshl_add_u64 v[228:229], v[218:219], 0, s[6:7]
	global_store_dword v[228:229], v226, off
	v_mov_b32_e32 v153, v189
	s_waitcnt vmcnt(63) expcnt(7) lgkmcnt(15)
	s_barrier
	v_lshl_add_u64 v[132:133], s[64:65], 0, v[164:165]
	v_lshlrev_b64 v[130:131], 1, v[168:169]
	v_lshlrev_b64 v[226:227], 14, v[166:167]
	v_lshl_add_u64 v[226:227], s[64:65], 0, v[226:227]
	v_lshl_add_u64 v[226:227], v[226:227], 0, v[130:131]
	v_mov_b32_e32 v228, v152
	v_mov_b32_e32 v229, v1
	v_lshl_add_u64 v[226:227], v[226:227], 0, v[228:229]
	s_mov_b64 s[6:7], 0xf640000
	v_lshl_add_u64 v[226:227], v[226:227], 0, s[6:7]
	global_load_dwordx4 v[234:237], v[226:227], off
	global_load_dwordx4 v[238:241], v[226:227], off offset:32
	global_load_dwordx4 v[242:245], v[226:227], off offset:64
	global_load_dwordx4 v[246:249], v[226:227], off offset:96
	v_lshl_add_u64 v[132:133], v[132:133], 0, v[130:131]
	v_lshlrev_b32_e32 v134, 4, v153
	v_and_b32_e32 v144, 0xf0, v134
	v_mov_b32_e32 v145, v1
	v_lshlrev_b32_e32 v134, 10, v153
	v_lshl_add_u64 v[132:133], v[132:133], 0, v[144:145]
	v_and_b32_e32 v134, 0x3c000, v134
	v_mov_b32_e32 v135, v1
	v_lshl_add_u64 v[172:173], v[132:133], 0, v[134:135]
	s_mov_b32 s6, 0xe640000
	v_add_co_u32_e64 v132, s[6:7], s6, v172
	v_bfe_u32 v145, v153, 4, 4
	s_nop 0
	v_addc_co_u32_e64 v133, s[6:7], 0, v173, s[6:7]
	s_mov_b32 s6, 0xe680000
	s_nop 0
	v_add_co_u32_e64 v136, s[6:7], s6, v172
	global_load_dwordx4 v[132:135], v[132:133], off
	s_nop 0
	v_addc_co_u32_e64 v137, s[6:7], 0, v173, s[6:7]
	s_mov_b32 s6, 0xe6c0000
	s_nop 0
	v_add_co_u32_e64 v140, s[6:7], s6, v172
	global_load_dwordx4 v[136:139], v[136:137], off
	s_nop 0
	v_addc_co_u32_e64 v141, s[6:7], 0, v173, s[6:7]
	s_mov_b32 s6, 0xe700000
	s_nop 0
	v_add_co_u32_e64 v168, s[6:7], s6, v172
	global_load_dwordx4 v[140:143], v[140:141], off
	s_nop 0
	v_addc_co_u32_e64 v169, s[6:7], 0, v173, s[6:7]
	s_mov_b32 s6, 0xe740000
	s_nop 0
	v_add_co_u32_e64 v192, s[6:7], s6, v172
	global_load_dwordx4 v[168:171], v[168:169], off
	s_nop 0
	v_addc_co_u32_e64 v193, s[6:7], 0, v173, s[6:7]
	s_mov_b32 s6, 0xe780000
	s_nop 0
	v_add_co_u32_e64 v196, s[6:7], s6, v172
	global_load_dwordx4 v[192:195], v[192:193], off
	s_nop 0
	v_addc_co_u32_e64 v197, s[6:7], 0, v173, s[6:7]
	s_mov_b32 s6, 0xe7c0000
	s_nop 0
	v_add_co_u32_e64 v208, s[6:7], s6, v172
	global_load_dwordx4 v[196:199], v[196:197], off
	s_nop 0
	v_addc_co_u32_e64 v209, s[6:7], 0, v173, s[6:7]
	s_mov_b32 s6, 0xe800000
	global_load_dwordx4 v[218:221], v[208:209], off
	v_add_co_u32_e64 v208, s[6:7], s6, v172
	v_mul_u32_u24_e32 v145, 0x108, v145
	s_nop 0
	v_addc_co_u32_e64 v209, s[6:7], 0, v173, s[6:7]
	global_load_dwordx4 v[222:225], v[208:209], off
	v_add3_u32 v153, v149, v144, v145
	v_mul_f32 v2, v2, v159
	v_mul_f32 v3, v3, v159
	v_mul_f32 v4, v4, v159
	v_mul_f32 v5, v5, v159
	v_mul_f32 v6, v6, v159
	v_mul_f32 v7, v7, v159
	v_mul_f32 v8, v8, v159
	v_mul_f32 v9, v9, v159
	v_mul_f32 v10, v10, v159
	v_mul_f32 v11, v11, v159
	v_mul_f32 v12, v12, v159
	v_mul_f32 v13, v13, v159
	v_mul_f32 v14, v14, v159
	v_mul_f32 v15, v15, v159
	v_mul_f32 v16, v16, v159
	v_mul_f32 v17, v17, v159
	v_mul_f32 v18, v18, v159
	v_mul_f32 v19, v19, v159
	v_mul_f32 v20, v20, v159
	v_mul_f32 v21, v21, v159
	v_mul_f32 v22, v22, v159
	v_mul_f32 v23, v23, v159
	v_mul_f32 v24, v24, v159
	v_mul_f32 v25, v25, v159
	v_mul_f32 v26, v26, v159
	v_mul_f32 v27, v27, v159
	v_mul_f32 v28, v28, v159
	v_mul_f32 v29, v29, v159
	v_mul_f32 v30, v30, v159
	v_mul_f32 v31, v31, v159
	v_mul_f32 v32, v32, v159
	v_mul_f32 v33, v33, v159
	v_mul_f32 v34, v34, v159
	v_mul_f32 v35, v35, v159
	v_mul_f32 v36, v36, v159
	v_mul_f32 v37, v37, v159
	v_mul_f32 v38, v38, v159
	v_mul_f32 v39, v39, v159
	v_mul_f32 v40, v40, v159
	v_mul_f32 v41, v41, v159
	v_mul_f32 v42, v42, v159
	v_mul_f32 v43, v43, v159
	v_mul_f32 v44, v44, v159
	v_mul_f32 v45, v45, v159
	v_mul_f32 v46, v46, v159
	v_mul_f32 v47, v47, v159
	v_mul_f32 v48, v48, v159
	v_mul_f32 v49, v49, v159
	v_mul_f32 v50, v50, v159
	v_mul_f32 v51, v51, v159
	v_mul_f32 v52, v52, v159
	v_mul_f32 v53, v53, v159
	v_mul_f32 v54, v54, v159
	v_mul_f32 v55, v55, v159
	v_mul_f32 v56, v56, v159
	v_mul_f32 v57, v57, v159
	v_mul_f32 v58, v58, v159
	v_mul_f32 v59, v59, v159
	v_mul_f32 v60, v60, v159
	v_mul_f32 v61, v61, v159
	v_mul_f32 v62, v62, v159
	v_mul_f32 v63, v63, v159
	v_mul_f32 v64, v64, v159
	v_mul_f32 v65, v65, v159
	v_mul_f32 v66, v66, v159
	v_mul_f32 v67, v67, v159
	v_mul_f32 v68, v68, v159
	v_mul_f32 v69, v69, v159
	v_mul_f32 v70, v70, v159
	v_mul_f32 v71, v71, v159
	v_mul_f32 v72, v72, v159
	v_mul_f32 v73, v73, v159
	v_mul_f32 v74, v74, v159
	v_mul_f32 v75, v75, v159
	v_mul_f32 v76, v76, v159
	v_mul_f32 v77, v77, v159
	v_mul_f32 v78, v78, v159
	v_mul_f32 v79, v79, v159
	v_mul_f32 v80, v80, v159
	v_mul_f32 v81, v81, v159
	v_mul_f32 v82, v82, v159
	v_mul_f32 v83, v83, v159
	v_mul_f32 v84, v84, v159
	v_mul_f32 v85, v85, v159
	v_mul_f32 v86, v86, v159
	v_mul_f32 v87, v87, v159
	v_mul_f32 v88, v88, v159
	v_mul_f32 v89, v89, v159
	v_mul_f32 v90, v90, v159
	v_mul_f32 v91, v91, v159
	v_mul_f32 v92, v92, v159
	v_mul_f32 v93, v93, v159
	v_mul_f32 v94, v94, v159
	v_mul_f32 v95, v95, v159
	v_mul_f32 v96, v96, v159
	v_mul_f32 v97, v97, v159
	v_mul_f32 v98, v98, v159
	v_mul_f32 v99, v99, v159
	v_mul_f32 v100, v100, v159
	v_mul_f32 v101, v101, v159
	v_mul_f32 v102, v102, v159
	v_mul_f32 v103, v103, v159
	v_mul_f32 v104, v104, v159
	v_mul_f32 v105, v105, v159
	v_mul_f32 v106, v106, v159
	v_mul_f32 v107, v107, v159
	v_mul_f32 v108, v108, v159
	v_mul_f32 v109, v109, v159
	v_mul_f32 v110, v110, v159
	v_mul_f32 v111, v111, v159
	v_mul_f32 v112, v112, v159
	v_mul_f32 v113, v113, v159
	v_mul_f32 v114, v114, v159
	v_mul_f32 v115, v115, v159
	v_mul_f32 v116, v116, v159
	v_mul_f32 v117, v117, v159
	v_mul_f32 v118, v118, v159
	v_mul_f32 v119, v119, v159
	v_mul_f32 v120, v120, v159
	v_mul_f32 v121, v121, v159
	v_mul_f32 v122, v122, v159
	v_mul_f32 v123, v123, v159
	v_mul_f32 v124, v124, v159
	v_mul_f32 v125, v125, v159
	v_mul_f32 v126, v126, v159
	v_mul_f32 v127, v127, v159
	v_mul_f32 v128, v128, v159
	v_mul_f32 v129, v129, v159
	s_waitcnt vmcnt(7)
	ds_write2_b64 v153, v[132:133], v[134:135] offset1:1
	v_add_u32_e32 v132, 0x1080, v153
	s_waitcnt vmcnt(6)
	ds_write2_b64 v132, v[136:137], v[138:139] offset1:1
	v_add_u32_e32 v132, 0x2100, v153
	s_waitcnt vmcnt(5)
	ds_write2_b64 v132, v[140:141], v[142:143] offset1:1
	v_add_u32_e32 v132, 0x3180, v153
	s_waitcnt vmcnt(4)
	ds_write2_b64 v132, v[168:169], v[170:171] offset1:1
	v_add_u32_e32 v132, 0x4200, v153
	s_waitcnt vmcnt(3)
	ds_write2_b64 v132, v[192:193], v[194:195] offset1:1
	v_add_u32_e32 v132, 0x5280, v153
	s_waitcnt vmcnt(2)
	ds_write2_b64 v132, v[196:197], v[198:199] offset1:1
	v_add_u32_e32 v132, 0x6300, v153
	s_waitcnt vmcnt(1)
	ds_write2_b64 v132, v[218:219], v[220:221] offset1:1
	v_add_u32_e32 v132, 0x7380, v153
	s_waitcnt vmcnt(0)
	ds_write2_b64 v132, v[222:223], v[224:225] offset1:1
	s_mov_b32 s6, 0xe840000
	v_add_co_u32_e64 v132, s[6:7], s6, v172
	s_nop 1
	v_addc_co_u32_e64 v133, s[6:7], 0, v173, s[6:7]
	s_mov_b32 s6, 0xe880000
	s_nop 0
	v_add_co_u32_e64 v136, s[6:7], s6, v172
	global_load_dwordx4 v[132:135], v[132:133], off
	s_nop 0
	v_addc_co_u32_e64 v137, s[6:7], 0, v173, s[6:7]
	s_mov_b32 s6, 0xe8c0000
	s_nop 0
	v_add_co_u32_e64 v140, s[6:7], s6, v172
	global_load_dwordx4 v[136:139], v[136:137], off
	s_nop 0
	v_addc_co_u32_e64 v141, s[6:7], 0, v173, s[6:7]
	s_mov_b32 s6, 0xe900000
	s_nop 0
	v_add_co_u32_e64 v144, s[6:7], s6, v172
	global_load_dwordx4 v[140:143], v[140:141], off
	s_nop 0
	v_addc_co_u32_e64 v145, s[6:7], 0, v173, s[6:7]
	s_mov_b32 s6, 0xe940000
	global_load_dwordx4 v[168:171], v[144:145], off
	v_add_co_u32_e64 v144, s[6:7], s6, v172
	s_nop 1
	v_addc_co_u32_e64 v145, s[6:7], 0, v173, s[6:7]
	s_mov_b32 s6, 0xe980000
	global_load_dwordx4 v[192:195], v[144:145], off
	v_add_co_u32_e64 v144, s[6:7], s6, v172
	s_nop 1
	v_addc_co_u32_e64 v145, s[6:7], 0, v173, s[6:7]
	s_mov_b32 s6, 0xe9c0000
	global_load_dwordx4 v[196:199], v[144:145], off
	v_add_co_u32_e64 v144, s[6:7], s6, v172
	s_nop 1
	v_addc_co_u32_e64 v145, s[6:7], 0, v173, s[6:7]
	s_mov_b32 s6, 0xea00000
	global_load_dwordx4 v[218:221], v[144:145], off
	v_add_co_u32_e64 v144, s[6:7], s6, v172
	s_nop 1
	v_addc_co_u32_e64 v145, s[6:7], 0, v173, s[6:7]
	global_load_dwordx4 v[222:225], v[144:145], off
	v_add_u32_e32 v144, 0x8400, v153
	s_waitcnt vmcnt(7)
	ds_write2_b64 v144, v[132:133], v[134:135] offset1:1
	v_add_u32_e32 v132, 0x9480, v153
	s_waitcnt vmcnt(6)
	ds_write2_b64 v132, v[136:137], v[138:139] offset1:1
	v_add_u32_e32 v132, 0xa500, v153
	s_waitcnt vmcnt(5)
	ds_write2_b64 v132, v[140:141], v[142:143] offset1:1
	v_add_u32_e32 v132, 0xb580, v153
	s_waitcnt vmcnt(4)
	ds_write2_b64 v132, v[168:169], v[170:171] offset1:1
	v_add_u32_e32 v132, 0xc600, v153
	s_waitcnt vmcnt(3)
	ds_write2_b64 v132, v[192:193], v[194:195] offset1:1
	v_add_u32_e32 v132, 0xd680, v153
	s_waitcnt vmcnt(2)
	ds_write2_b64 v132, v[196:197], v[198:199] offset1:1
	v_add_u32_e32 v132, 0xe700, v153
	s_waitcnt vmcnt(1)
	ds_write2_b64 v132, v[218:219], v[220:221] offset1:1
	v_add_u32_e32 v132, 0xf780, v153
	s_waitcnt vmcnt(0)
	ds_write2_b64 v132, v[222:223], v[224:225] offset1:1
	s_waitcnt lgkmcnt(0)
	s_barrier
	v_lshlrev_b64 v[132:133], 14, v[166:167]
	v_lshl_add_u64 v[132:133], s[64:65], 0, v[132:133]
	v_lshl_add_u64 v[130:131], v[132:133], 0, v[130:131]
	v_mov_b32_e32 v153, v1
	v_lshl_add_u64 v[134:135], v[130:131], 0, v[152:153]
	s_mov_b32 s6, 0xf640000
	v_add_co_u32_e64 v130, s[6:7], s6, v134
	s_nop 1
	v_addc_co_u32_e64 v131, s[6:7], 0, v135, s[6:7]
	s_mov_b64 s[6:7], 0xf640000
	v_lshl_add_u64 v[142:143], v[134:135], 0, s[6:7]
	v_mov_b32_e32 v130, v234
	v_mov_b32_e32 v131, v235
	v_mov_b32_e32 v132, v236
	v_mov_b32_e32 v133, v237
	v_mov_b32_e32 v134, v238
	v_mov_b32_e32 v135, v239
	v_mov_b32_e32 v136, v240
	v_mov_b32_e32 v137, v241
	v_mov_b32_e32 v138, v242
	v_mov_b32_e32 v139, v243
	v_mov_b32_e32 v140, v244
	v_mov_b32_e32 v141, v245
	v_mov_b32_e32 v166, v246
	v_mov_b32_e32 v167, v247
	v_mov_b32_e32 v168, v248
	v_mov_b32_e32 v169, v249
	global_load_dwordx4 v[234:237], v[142:143], off offset:128
	global_load_dwordx4 v[238:241], v[142:143], off offset:160
	global_load_dwordx4 v[242:245], v[142:143], off offset:192
	global_load_dwordx4 v[246:249], v[142:143], off offset:224
	v_fma_f32 v144, 0, v191, v190
	v_add_f32_e32 v145, v190, v191
	v_exp_f32_e32 v144, v144
	v_exp_f32_e32 v145, v145
	v_fmamk_f32 v153, v191, 0x42480000, v190
	s_waitcnt vmcnt(4)
	v_lshlrev_b32_e32 v170, 16, v130
	v_and_b32_e32 v171, 0xffff0000, v130
	v_fma_f32 v130, 2.0, v191, v190
	v_pk_mul_f32 v[144:145], v[144:145], v[170:171]
	v_exp_f32_e32 v170, v130
	v_fmamk_f32 v130, v191, 0x40400000, v190
	v_exp_f32_e32 v171, v130
	v_cvt_pk_bf16_f32 v130, v144, v145
	v_lshlrev_b32_e32 v144, 16, v131
	v_and_b32_e32 v145, 0xffff0000, v131
	v_fma_f32 v131, 4.0, v191, v190
	v_pk_mul_f32 v[144:145], v[170:171], v[144:145]
	v_exp_f32_e32 v170, v131
	v_fmamk_f32 v131, v191, 0x40a00000, v190
	v_exp_f32_e32 v171, v131
	v_cvt_pk_bf16_f32 v131, v144, v145
	v_lshlrev_b32_e32 v144, 16, v132
	v_and_b32_e32 v145, 0xffff0000, v132
	v_fmamk_f32 v132, v191, 0x40c00000, v190
	v_pk_mul_f32 v[144:145], v[170:171], v[144:145]
	v_exp_f32_e32 v170, v132
	v_fmamk_f32 v132, v191, 0x40e00000, v190
	v_exp_f32_e32 v171, v132
	v_cvt_pk_bf16_f32 v132, v144, v145
	v_lshlrev_b32_e32 v144, 16, v133
	v_and_b32_e32 v145, 0xffff0000, v133
	v_fmamk_f32 v133, v191, 0x41800000, v190
	v_pk_mul_f32 v[144:145], v[170:171], v[144:145]
	v_exp_f32_e32 v170, v133
	v_fmamk_f32 v133, v191, 0x41880000, v190
	v_exp_f32_e32 v171, v133
	v_cvt_pk_bf16_f32 v133, v144, v145
	s_waitcnt vmcnt(4)
	v_lshlrev_b32_e32 v144, 16, v134
	v_and_b32_e32 v145, 0xffff0000, v134
	v_fmamk_f32 v134, v191, 0x41900000, v190
	v_pk_mul_f32 v[144:145], v[170:171], v[144:145]
	v_exp_f32_e32 v170, v134
	v_fmamk_f32 v134, v191, 0x41980000, v190
	v_exp_f32_e32 v171, v134
	v_cvt_pk_bf16_f32 v134, v144, v145
	v_lshlrev_b32_e32 v144, 16, v135
	v_and_b32_e32 v145, 0xffff0000, v135
	v_fmamk_f32 v135, v191, 0x41a00000, v190
	v_pk_mul_f32 v[144:145], v[170:171], v[144:145]
	v_exp_f32_e32 v170, v135
	v_fmamk_f32 v135, v191, 0x41a80000, v190
	v_exp_f32_e32 v171, v135
	v_cvt_pk_bf16_f32 v135, v144, v145
	v_lshlrev_b32_e32 v144, 16, v136
	v_and_b32_e32 v145, 0xffff0000, v136
	v_fmamk_f32 v136, v191, 0x41b00000, v190
	v_pk_mul_f32 v[144:145], v[170:171], v[144:145]
	v_exp_f32_e32 v170, v136
	v_fmamk_f32 v136, v191, 0x41b80000, v190
	v_exp_f32_e32 v171, v136
	v_cvt_pk_bf16_f32 v136, v144, v145
	v_lshlrev_b32_e32 v144, 16, v137
	v_and_b32_e32 v145, 0xffff0000, v137
	v_fmamk_f32 v137, v191, 0x42000000, v190
	v_pk_mul_f32 v[144:145], v[170:171], v[144:145]
	v_exp_f32_e32 v170, v137
	v_fmamk_f32 v137, v191, 0x42040000, v190
	v_exp_f32_e32 v171, v137
	v_cvt_pk_bf16_f32 v137, v144, v145
	s_waitcnt vmcnt(4)
	v_lshlrev_b32_e32 v144, 16, v138
	v_and_b32_e32 v145, 0xffff0000, v138
	v_fmamk_f32 v138, v191, 0x42080000, v190
	v_pk_mul_f32 v[144:145], v[170:171], v[144:145]
	v_exp_f32_e32 v170, v138
	v_fmamk_f32 v138, v191, 0x420c0000, v190
	v_exp_f32_e32 v171, v138
	v_cvt_pk_bf16_f32 v138, v144, v145
	v_lshlrev_b32_e32 v144, 16, v139
	v_and_b32_e32 v145, 0xffff0000, v139
	v_fmamk_f32 v139, v191, 0x42100000, v190
	v_pk_mul_f32 v[144:145], v[170:171], v[144:145]
	v_exp_f32_e32 v170, v139
	v_fmamk_f32 v139, v191, 0x42140000, v190
	v_exp_f32_e32 v171, v139
	v_cvt_pk_bf16_f32 v139, v144, v145
	v_lshlrev_b32_e32 v144, 16, v140
	v_and_b32_e32 v145, 0xffff0000, v140
	v_fmamk_f32 v140, v191, 0x42180000, v190
	v_pk_mul_f32 v[144:145], v[170:171], v[144:145]
	v_exp_f32_e32 v170, v140
	v_fmamk_f32 v140, v191, 0x421c0000, v190
	v_exp_f32_e32 v171, v140
	v_cvt_pk_bf16_f32 v140, v144, v145
	v_lshlrev_b32_e32 v144, 16, v141
	v_and_b32_e32 v145, 0xffff0000, v141
	v_fmamk_f32 v141, v191, 0x42400000, v190
	v_pk_mul_f32 v[144:145], v[170:171], v[144:145]
	v_exp_f32_e32 v170, v141
	v_fmamk_f32 v141, v191, 0x42440000, v190
	v_exp_f32_e32 v171, v141
	v_cvt_pk_bf16_f32 v141, v144, v145
	s_waitcnt vmcnt(4)
	v_lshlrev_b32_e32 v144, 16, v166
	v_and_b32_e32 v145, 0xffff0000, v166
	v_pk_mul_f32 v[144:145], v[170:171], v[144:145]
	v_exp_f32_e32 v170, v153
	v_fmamk_f32 v153, v191, 0x424c0000, v190
	v_exp_f32_e32 v171, v153
	v_cvt_pk_bf16_f32 v166, v144, v145
	v_lshlrev_b32_e32 v144, 16, v167
	v_and_b32_e32 v145, 0xffff0000, v167
	v_fmamk_f32 v153, v191, 0x42500000, v190
	v_pk_mul_f32 v[144:145], v[170:171], v[144:145]
	v_exp_f32_e32 v170, v153
	v_fmamk_f32 v153, v191, 0x42540000, v190
	v_exp_f32_e32 v171, v153
	v_cvt_pk_bf16_f32 v167, v144, v145
	v_lshlrev_b32_e32 v144, 16, v168
	v_and_b32_e32 v145, 0xffff0000, v168
	v_fmamk_f32 v153, v191, 0x42580000, v190
	v_pk_mul_f32 v[144:145], v[170:171], v[144:145]
	v_exp_f32_e32 v170, v153
	v_fmamk_f32 v153, v191, 0x425c0000, v190
	v_exp_f32_e32 v171, v153
	v_cvt_pk_bf16_f32 v168, v144, v145
	v_lshlrev_b32_e32 v144, 16, v169
	v_and_b32_e32 v145, 0xffff0000, v169
	v_pk_mul_f32 v[144:145], v[170:171], v[144:145]
	s_nop 0
	v_cvt_pk_bf16_f32 v169, v144, v145
	ds_read2_b64 v[170:173], v179 offset1:1
	ds_read2_b64 v[192:195], v179 offset0:4 offset1:5
	ds_read2_b64 v[196:199], v179 offset0:8 offset1:9
	ds_read2_b64 v[218:221], v179 offset0:12 offset1:13
	s_waitcnt lgkmcnt(3)
	v_mfma_f32_32x32x16_bf16 v[2:17], v[170:173], v[130:133], v[2:17]
	v_add_u32_e32 v144, 0x2100, v179
	ds_read2_b64 v[170:173], v144 offset1:1
	s_waitcnt lgkmcnt(3)
	v_mfma_f32_32x32x16_bf16 v[2:17], v[192:195], v[134:137], v[2:17]
	v_add_u32_e32 v144, 0x2120, v179
	ds_read2_b64 v[192:195], v144 offset1:1
	s_waitcnt lgkmcnt(3)
	v_mfma_f32_32x32x16_bf16 v[2:17], v[196:199], v[138:141], v[2:17]
	v_add_u32_e32 v144, 0x2140, v179
	ds_read2_b64 v[196:199], v144 offset1:1
	s_waitcnt lgkmcnt(3)
	v_mfma_f32_32x32x16_bf16 v[2:17], v[218:221], v[166:169], v[2:17]
	v_add_u32_e32 v144, 0x2160, v179
	ds_read2_b64 v[218:221], v144 offset1:1
	s_waitcnt lgkmcnt(3)
	v_mfma_f32_32x32x16_bf16 v[18:33], v[170:173], v[130:133], v[18:33]
	v_add_u32_e32 v144, 0x4200, v179
	ds_read2_b64 v[170:173], v144 offset1:1
	s_waitcnt lgkmcnt(3)
	v_mfma_f32_32x32x16_bf16 v[18:33], v[192:195], v[134:137], v[18:33]
	v_add_u32_e32 v144, 0x4220, v179
	ds_read2_b64 v[192:195], v144 offset1:1
	s_waitcnt lgkmcnt(3)
	v_mfma_f32_32x32x16_bf16 v[18:33], v[196:199], v[138:141], v[18:33]
	v_add_u32_e32 v144, 0x4240, v179
	ds_read2_b64 v[196:199], v144 offset1:1
	s_waitcnt lgkmcnt(3)
	v_mfma_f32_32x32x16_bf16 v[18:33], v[218:221], v[166:169], v[18:33]
	v_add_u32_e32 v144, 0x4260, v179
	ds_read2_b64 v[218:221], v144 offset1:1
	s_waitcnt lgkmcnt(3)
	v_mfma_f32_32x32x16_bf16 v[34:49], v[170:173], v[130:133], v[34:49]
	v_add_u32_e32 v144, 0x6300, v179
	ds_read2_b64 v[170:173], v144 offset1:1
	s_waitcnt lgkmcnt(3)
	v_mfma_f32_32x32x16_bf16 v[34:49], v[192:195], v[134:137], v[34:49]
	v_add_u32_e32 v144, 0x6320, v179
	ds_read2_b64 v[192:195], v144 offset1:1
	s_waitcnt lgkmcnt(3)
	v_mfma_f32_32x32x16_bf16 v[34:49], v[196:199], v[138:141], v[34:49]
	v_add_u32_e32 v144, 0x6340, v179
	ds_read2_b64 v[196:199], v144 offset1:1
	s_waitcnt lgkmcnt(3)
	v_mfma_f32_32x32x16_bf16 v[34:49], v[218:221], v[166:169], v[34:49]
	v_add_u32_e32 v144, 0x6360, v179
	ds_read2_b64 v[218:221], v144 offset1:1
	s_waitcnt lgkmcnt(3)
	v_mfma_f32_32x32x16_bf16 v[50:65], v[170:173], v[130:133], v[50:65]
	v_add_u32_e32 v144, 0x8400, v179
	ds_read2_b64 v[170:173], v144 offset1:1
	s_waitcnt lgkmcnt(3)
	v_mfma_f32_32x32x16_bf16 v[50:65], v[192:195], v[134:137], v[50:65]
	v_add_u32_e32 v144, 0x8420, v179
	ds_read2_b64 v[192:195], v144 offset1:1
	s_waitcnt lgkmcnt(3)
	v_mfma_f32_32x32x16_bf16 v[50:65], v[196:199], v[138:141], v[50:65]
	v_add_u32_e32 v144, 0x8440, v179
	ds_read2_b64 v[196:199], v144 offset1:1
	s_waitcnt lgkmcnt(3)
	v_mfma_f32_32x32x16_bf16 v[50:65], v[218:221], v[166:169], v[50:65]
	v_add_u32_e32 v144, 0x8460, v179
	ds_read2_b64 v[218:221], v144 offset1:1
	s_waitcnt lgkmcnt(3)
	v_mfma_f32_32x32x16_bf16 v[66:81], v[170:173], v[130:133], v[66:81]
	v_add_u32_e32 v144, 0xa500, v179
	ds_read2_b64 v[170:173], v144 offset1:1
	s_waitcnt lgkmcnt(3)
	v_mfma_f32_32x32x16_bf16 v[66:81], v[192:195], v[134:137], v[66:81]
	v_add_u32_e32 v144, 0xa520, v179
	ds_read2_b64 v[192:195], v144 offset1:1
	s_waitcnt lgkmcnt(3)
	v_mfma_f32_32x32x16_bf16 v[66:81], v[196:199], v[138:141], v[66:81]
	v_add_u32_e32 v144, 0xa540, v179
	ds_read2_b64 v[196:199], v144 offset1:1
	s_waitcnt lgkmcnt(3)
	v_mfma_f32_32x32x16_bf16 v[66:81], v[218:221], v[166:169], v[66:81]
	v_add_u32_e32 v144, 0xa560, v179
	ds_read2_b64 v[218:221], v144 offset1:1
	s_waitcnt lgkmcnt(3)
	v_mfma_f32_32x32x16_bf16 v[82:97], v[170:173], v[130:133], v[82:97]
	v_add_u32_e32 v144, 0xc600, v179
	ds_read2_b64 v[170:173], v144 offset1:1
	s_waitcnt lgkmcnt(3)
	v_mfma_f32_32x32x16_bf16 v[82:97], v[192:195], v[134:137], v[82:97]
	v_add_u32_e32 v144, 0xc620, v179
	ds_read2_b64 v[192:195], v144 offset1:1
	s_waitcnt lgkmcnt(3)
	v_mfma_f32_32x32x16_bf16 v[82:97], v[196:199], v[138:141], v[82:97]
	v_add_u32_e32 v144, 0xc640, v179
	ds_read2_b64 v[196:199], v144 offset1:1
	s_waitcnt lgkmcnt(3)
	v_mfma_f32_32x32x16_bf16 v[82:97], v[218:221], v[166:169], v[82:97]
	v_add_u32_e32 v144, 0xc660, v179
	ds_read2_b64 v[218:221], v144 offset1:1
	s_waitcnt lgkmcnt(3)
	v_mfma_f32_32x32x16_bf16 v[98:113], v[170:173], v[130:133], v[98:113]
	v_add_u32_e32 v144, 0xe700, v179
	ds_read2_b64 v[170:173], v144 offset1:1
	s_waitcnt lgkmcnt(3)
	v_mfma_f32_32x32x16_bf16 v[98:113], v[192:195], v[134:137], v[98:113]
	v_add_u32_e32 v144, 0xe720, v179
	ds_read2_b64 v[192:195], v144 offset1:1
	s_waitcnt lgkmcnt(3)
	v_mfma_f32_32x32x16_bf16 v[98:113], v[196:199], v[138:141], v[98:113]
	v_add_u32_e32 v144, 0xe740, v179
	ds_read2_b64 v[196:199], v144 offset1:1
	s_waitcnt lgkmcnt(3)
	v_mfma_f32_32x32x16_bf16 v[98:113], v[218:221], v[166:169], v[98:113]
	v_add_u32_e32 v144, 0xe760, v179
	ds_read2_b64 v[218:221], v144 offset1:1
	s_waitcnt lgkmcnt(3)
	v_mfma_f32_32x32x16_bf16 v[114:129], v[170:173], v[130:133], v[114:129]
	s_waitcnt lgkmcnt(2)
	v_mfma_f32_32x32x16_bf16 v[114:129], v[192:195], v[134:137], v[114:129]
	s_waitcnt lgkmcnt(1)
	v_mfma_f32_32x32x16_bf16 v[114:129], v[196:199], v[138:141], v[114:129]
	s_waitcnt lgkmcnt(0)
	v_mfma_f32_32x32x16_bf16 v[114:129], v[218:221], v[166:169], v[114:129]
	v_fmamk_f32 v134, v191, 0x42800000, v190
	v_fmamk_f32 v135, v191, 0x42820000, v190
	v_exp_f32_e32 v134, v134
	v_exp_f32_e32 v135, v135
	v_fmamk_f32 v138, v191, 0x42a00000, v190
	v_fmamk_f32 v139, v191, 0x42a20000, v190
	v_exp_f32_e32 v138, v138
	v_exp_f32_e32 v139, v139
	v_fmamk_f32 v144, v191, 0x42c00000, v190
	v_fmamk_f32 v145, v191, 0x42c20000, v190
	v_exp_f32_e32 v144, v144
	v_exp_f32_e32 v145, v145
	v_fmamk_f32 v153, v191, 0x42e00000, v190
	s_waitcnt vmcnt(0)
	v_mov_b32_e32 v130, v234
	v_mov_b32_e32 v131, v235
	v_mov_b32_e32 v132, v236
	v_mov_b32_e32 v133, v237
	v_lshlrev_b32_e32 v136, 16, v130
	v_and_b32_e32 v137, 0xffff0000, v130
	v_pk_mul_f32 v[134:135], v[134:135], v[136:137]
	v_lshlrev_b32_e32 v136, 16, v131
	v_cvt_pk_bf16_f32 v130, v134, v135
	v_fmamk_f32 v134, v191, 0x42840000, v190
	v_fmamk_f32 v135, v191, 0x42860000, v190
	v_exp_f32_e32 v134, v134
	v_exp_f32_e32 v135, v135
	v_and_b32_e32 v137, 0xffff0000, v131
	v_pk_mul_f32 v[134:135], v[134:135], v[136:137]
	s_nop 0
	v_cvt_pk_bf16_f32 v131, v134, v135
	v_fmamk_f32 v134, v191, 0x42880000, v190
	v_fmamk_f32 v135, v191, 0x428a0000, v190
	v_exp_f32_e32 v134, v134
	v_exp_f32_e32 v135, v135
	v_lshlrev_b32_e32 v136, 16, v132
	v_and_b32_e32 v137, 0xffff0000, v132
	v_pk_mul_f32 v[134:135], v[134:135], v[136:137]
	s_nop 0
	v_cvt_pk_bf16_f32 v132, v134, v135
	v_fmamk_f32 v134, v191, 0x428c0000, v190
	v_fmamk_f32 v135, v191, 0x428e0000, v190
	v_exp_f32_e32 v134, v134
	v_exp_f32_e32 v135, v135
	v_lshlrev_b32_e32 v136, 16, v133
	v_and_b32_e32 v137, 0xffff0000, v133
	v_pk_mul_f32 v[134:135], v[134:135], v[136:137]
	s_nop 0
	v_cvt_pk_bf16_f32 v133, v134, v135
	s_waitcnt vmcnt(0)
	v_mov_b32_e32 v134, v238
	v_mov_b32_e32 v135, v239
	v_mov_b32_e32 v136, v240
	v_mov_b32_e32 v137, v241
	v_lshlrev_b32_e32 v140, 16, v134
	v_and_b32_e32 v141, 0xffff0000, v134
	v_pk_mul_f32 v[138:139], v[138:139], v[140:141]
	v_lshlrev_b32_e32 v140, 16, v135
	v_cvt_pk_bf16_f32 v134, v138, v139
	v_fmamk_f32 v138, v191, 0x42a40000, v190
	v_fmamk_f32 v139, v191, 0x42a60000, v190
	v_exp_f32_e32 v138, v138
	v_exp_f32_e32 v139, v139
	v_and_b32_e32 v141, 0xffff0000, v135
	v_pk_mul_f32 v[138:139], v[138:139], v[140:141]
	s_nop 0
	v_cvt_pk_bf16_f32 v135, v138, v139
	v_fmamk_f32 v138, v191, 0x42a80000, v190
	v_fmamk_f32 v139, v191, 0x42aa0000, v190
	v_exp_f32_e32 v138, v138
	v_exp_f32_e32 v139, v139
	v_lshlrev_b32_e32 v140, 16, v136
	v_and_b32_e32 v141, 0xffff0000, v136
	v_pk_mul_f32 v[138:139], v[138:139], v[140:141]
	s_nop 0
	v_cvt_pk_bf16_f32 v136, v138, v139
	v_fmamk_f32 v138, v191, 0x42ac0000, v190
	v_fmamk_f32 v139, v191, 0x42ae0000, v190
	v_exp_f32_e32 v138, v138
	v_exp_f32_e32 v139, v139
	v_lshlrev_b32_e32 v140, 16, v137
	v_and_b32_e32 v141, 0xffff0000, v137
	v_pk_mul_f32 v[138:139], v[138:139], v[140:141]
	s_nop 0
	v_cvt_pk_bf16_f32 v137, v138, v139
	s_waitcnt vmcnt(0)
	v_mov_b32_e32 v138, v242
	v_mov_b32_e32 v139, v243
	v_mov_b32_e32 v140, v244
	v_mov_b32_e32 v141, v245
	v_lshlrev_b32_e32 v166, 16, v138
	v_and_b32_e32 v167, 0xffff0000, v138
	v_pk_mul_f32 v[144:145], v[144:145], v[166:167]
	v_lshlrev_b32_e32 v166, 16, v139
	v_cvt_pk_bf16_f32 v138, v144, v145
	v_fmamk_f32 v144, v191, 0x42c40000, v190
	v_fmamk_f32 v145, v191, 0x42c60000, v190
	v_exp_f32_e32 v144, v144
	v_exp_f32_e32 v145, v145
	v_and_b32_e32 v167, 0xffff0000, v139
	v_pk_mul_f32 v[144:145], v[144:145], v[166:167]
	s_nop 0
	v_cvt_pk_bf16_f32 v139, v144, v145
	v_fmamk_f32 v144, v191, 0x42c80000, v190
	v_fmamk_f32 v145, v191, 0x42ca0000, v190
	v_exp_f32_e32 v144, v144
	v_exp_f32_e32 v145, v145
	v_lshlrev_b32_e32 v166, 16, v140
	v_and_b32_e32 v167, 0xffff0000, v140
	v_pk_mul_f32 v[144:145], v[144:145], v[166:167]
	s_nop 0
	v_cvt_pk_bf16_f32 v140, v144, v145
	v_fmamk_f32 v144, v191, 0x42cc0000, v190
	v_fmamk_f32 v145, v191, 0x42ce0000, v190
	v_exp_f32_e32 v144, v144
	v_exp_f32_e32 v145, v145
	v_lshlrev_b32_e32 v166, 16, v141
	v_and_b32_e32 v167, 0xffff0000, v141
	v_pk_mul_f32 v[144:145], v[144:145], v[166:167]
	s_nop 0
	v_cvt_pk_bf16_f32 v141, v144, v145
	v_exp_f32_e32 v166, v153
	v_fmamk_f32 v153, v191, 0x42e20000, v190
	v_exp_f32_e32 v167, v153
	v_fmamk_f32 v153, v191, 0x42e40000, v190
	s_waitcnt vmcnt(0)
	v_mov_b32_e32 v142, v246
	v_mov_b32_e32 v143, v247
	v_mov_b32_e32 v144, v248
	v_mov_b32_e32 v145, v249
	v_lshlrev_b32_e32 v168, 16, v142
	v_and_b32_e32 v169, 0xffff0000, v142
	v_pk_mul_f32 v[166:167], v[166:167], v[168:169]
	v_lshlrev_b32_e32 v168, 16, v143
	v_cvt_pk_bf16_f32 v142, v166, v167
	v_exp_f32_e32 v166, v153
	v_fmamk_f32 v153, v191, 0x42e60000, v190
	v_exp_f32_e32 v167, v153
	v_and_b32_e32 v169, 0xffff0000, v143
	v_fmamk_f32 v153, v191, 0x42e80000, v190
	v_pk_mul_f32 v[166:167], v[166:167], v[168:169]
	s_nop 0
	v_cvt_pk_bf16_f32 v143, v166, v167
	v_exp_f32_e32 v166, v153
	v_fmamk_f32 v153, v191, 0x42ea0000, v190
	v_exp_f32_e32 v167, v153
	v_lshlrev_b32_e32 v168, 16, v144
	v_and_b32_e32 v169, 0xffff0000, v144
	v_fmamk_f32 v153, v191, 0x42ec0000, v190
	v_pk_mul_f32 v[166:167], v[166:167], v[168:169]
	v_fmac_f32_e32 v190, 0x42ee0000, v191
	v_cvt_pk_bf16_f32 v144, v166, v167
	v_exp_f32_e32 v166, v153
	v_exp_f32_e32 v167, v190
	v_lshlrev_b32_e32 v168, 16, v145
	v_and_b32_e32 v169, 0xffff0000, v145
	v_pk_mul_f32 v[166:167], v[166:167], v[168:169]
	s_nop 0
	v_cvt_pk_bf16_f32 v145, v166, v167
	ds_read2_b64 v[166:169], v179 offset0:16 offset1:17
	ds_read2_b64 v[170:173], v179 offset0:20 offset1:21
	ds_read2_b64 v[190:193], v179 offset0:24 offset1:25
	ds_read2_b64 v[194:197], v179 offset0:28 offset1:29
	s_waitcnt lgkmcnt(3)
	v_mfma_f32_32x32x16_bf16 v[2:17], v[166:169], v[130:133], v[2:17]
	v_add_u32_e32 v153, 0x2180, v179
	ds_read2_b64 v[166:169], v153 offset1:1
	s_waitcnt lgkmcnt(3)
	v_mfma_f32_32x32x16_bf16 v[2:17], v[170:173], v[134:137], v[2:17]
	v_add_u32_e32 v153, 0x21a0, v179
	ds_read2_b64 v[170:173], v153 offset1:1
	s_waitcnt lgkmcnt(3)
	v_mfma_f32_32x32x16_bf16 v[2:17], v[190:193], v[138:141], v[2:17]
	v_add_u32_e32 v153, 0x21c0, v179
	ds_read2_b64 v[190:193], v153 offset1:1
	s_waitcnt lgkmcnt(3)
	v_mfma_f32_32x32x16_bf16 v[2:17], v[194:197], v[142:145], v[2:17]
	v_add_u32_e32 v153, 0x21e0, v179
	ds_read2_b64 v[194:197], v153 offset1:1
	s_waitcnt lgkmcnt(3)
	v_mfma_f32_32x32x16_bf16 v[18:33], v[166:169], v[130:133], v[18:33]
	v_add_u32_e32 v153, 0x4280, v179
	ds_read2_b64 v[166:169], v153 offset1:1
	s_waitcnt lgkmcnt(3)
	v_mfma_f32_32x32x16_bf16 v[18:33], v[170:173], v[134:137], v[18:33]
	v_add_u32_e32 v153, 0x42a0, v179
	ds_read2_b64 v[170:173], v153 offset1:1
	s_waitcnt lgkmcnt(3)
	v_mfma_f32_32x32x16_bf16 v[18:33], v[190:193], v[138:141], v[18:33]
	v_add_u32_e32 v153, 0x42c0, v179
	ds_read2_b64 v[190:193], v153 offset1:1
	s_waitcnt lgkmcnt(3)
	v_mfma_f32_32x32x16_bf16 v[18:33], v[194:197], v[142:145], v[18:33]
	v_add_u32_e32 v153, 0x42e0, v179
	ds_read2_b64 v[194:197], v153 offset1:1
	s_waitcnt lgkmcnt(3)
	v_mfma_f32_32x32x16_bf16 v[34:49], v[166:169], v[130:133], v[34:49]
	v_add_u32_e32 v153, 0x6380, v179
	ds_read2_b64 v[166:169], v153 offset1:1
	s_waitcnt lgkmcnt(3)
	v_mfma_f32_32x32x16_bf16 v[34:49], v[170:173], v[134:137], v[34:49]
	v_add_u32_e32 v153, 0x63a0, v179
	ds_read2_b64 v[170:173], v153 offset1:1
	s_waitcnt lgkmcnt(3)
	v_mfma_f32_32x32x16_bf16 v[34:49], v[190:193], v[138:141], v[34:49]
	v_add_u32_e32 v153, 0x63c0, v179
	ds_read2_b64 v[190:193], v153 offset1:1
	s_waitcnt lgkmcnt(3)
	v_mfma_f32_32x32x16_bf16 v[34:49], v[194:197], v[142:145], v[34:49]
	v_add_u32_e32 v153, 0x63e0, v179
	ds_read2_b64 v[194:197], v153 offset1:1
	s_waitcnt lgkmcnt(3)
	v_mfma_f32_32x32x16_bf16 v[50:65], v[166:169], v[130:133], v[50:65]
	v_add_u32_e32 v153, 0x8480, v179
	ds_read2_b64 v[166:169], v153 offset1:1
	s_waitcnt lgkmcnt(3)
	v_mfma_f32_32x32x16_bf16 v[50:65], v[170:173], v[134:137], v[50:65]
	v_add_u32_e32 v153, 0x84a0, v179
	ds_read2_b64 v[170:173], v153 offset1:1
	s_waitcnt lgkmcnt(3)
	v_mfma_f32_32x32x16_bf16 v[50:65], v[190:193], v[138:141], v[50:65]
	v_add_u32_e32 v153, 0x84c0, v179
	ds_read2_b64 v[190:193], v153 offset1:1
	s_waitcnt lgkmcnt(3)
	v_mfma_f32_32x32x16_bf16 v[50:65], v[194:197], v[142:145], v[50:65]
	v_add_u32_e32 v153, 0x84e0, v179
	ds_read2_b64 v[194:197], v153 offset1:1
	s_waitcnt lgkmcnt(3)
	v_mfma_f32_32x32x16_bf16 v[66:81], v[166:169], v[130:133], v[66:81]
	v_add_u32_e32 v153, 0xa580, v179
	ds_read2_b64 v[166:169], v153 offset1:1
	s_waitcnt lgkmcnt(3)
	v_mfma_f32_32x32x16_bf16 v[66:81], v[170:173], v[134:137], v[66:81]
	v_add_u32_e32 v153, 0xa5a0, v179
	ds_read2_b64 v[170:173], v153 offset1:1
	s_waitcnt lgkmcnt(3)
	v_mfma_f32_32x32x16_bf16 v[66:81], v[190:193], v[138:141], v[66:81]
	v_add_u32_e32 v153, 0xa5c0, v179
	ds_read2_b64 v[190:193], v153 offset1:1
	s_waitcnt lgkmcnt(3)
	v_mfma_f32_32x32x16_bf16 v[66:81], v[194:197], v[142:145], v[66:81]
	v_add_u32_e32 v153, 0xa5e0, v179
	ds_read2_b64 v[194:197], v153 offset1:1
	s_waitcnt lgkmcnt(3)
	v_mfma_f32_32x32x16_bf16 v[82:97], v[166:169], v[130:133], v[82:97]
	v_add_u32_e32 v153, 0xc680, v179
	ds_read2_b64 v[166:169], v153 offset1:1
	s_waitcnt lgkmcnt(3)
	v_mfma_f32_32x32x16_bf16 v[82:97], v[170:173], v[134:137], v[82:97]
	v_add_u32_e32 v153, 0xc6a0, v179
	ds_read2_b64 v[170:173], v153 offset1:1
	s_waitcnt lgkmcnt(3)
	v_mfma_f32_32x32x16_bf16 v[82:97], v[190:193], v[138:141], v[82:97]
	v_add_u32_e32 v153, 0xc6c0, v179
	ds_read2_b64 v[190:193], v153 offset1:1
	s_waitcnt lgkmcnt(3)
	v_mfma_f32_32x32x16_bf16 v[82:97], v[194:197], v[142:145], v[82:97]
	v_add_u32_e32 v153, 0xc6e0, v179
	ds_read2_b64 v[194:197], v153 offset1:1
	s_waitcnt lgkmcnt(3)
	v_mfma_f32_32x32x16_bf16 v[98:113], v[166:169], v[130:133], v[98:113]
	v_add_u32_e32 v153, 0xe780, v179
	ds_read2_b64 v[166:169], v153 offset1:1
	s_waitcnt lgkmcnt(3)
	v_mfma_f32_32x32x16_bf16 v[98:113], v[170:173], v[134:137], v[98:113]
	v_add_u32_e32 v153, 0xe7a0, v179
	ds_read2_b64 v[170:173], v153 offset1:1
	s_waitcnt lgkmcnt(3)
	v_mfma_f32_32x32x16_bf16 v[98:113], v[190:193], v[138:141], v[98:113]
	v_add_u32_e32 v153, 0xe7c0, v179
	ds_read2_b64 v[190:193], v153 offset1:1
	s_waitcnt lgkmcnt(3)
	v_mfma_f32_32x32x16_bf16 v[98:113], v[194:197], v[142:145], v[98:113]
	v_add_u32_e32 v153, 0xe7e0, v179
	ds_read2_b64 v[194:197], v153 offset1:1
	s_waitcnt lgkmcnt(3)
	v_mfma_f32_32x32x16_bf16 v[114:129], v[166:169], v[130:133], v[114:129]
	s_waitcnt lgkmcnt(2)
	v_mfma_f32_32x32x16_bf16 v[114:129], v[170:173], v[134:137], v[114:129]
	s_waitcnt lgkmcnt(1)
	v_mfma_f32_32x32x16_bf16 v[114:129], v[190:193], v[138:141], v[114:129]
	s_waitcnt lgkmcnt(0)
	v_mfma_f32_32x32x16_bf16 v[114:129], v[194:197], v[142:145], v[114:129]
	s_add_i32 s66, s66, 1
	s_add_i32 s67, s67, -1
	s_cmp_eq_u32 s67, -1
	s_cbranch_scc0 .LBB0_327
	s_and_b64 vcc, exec, s[4:5]
	s_mov_b64 s[4:5], -1
	s_cbranch_vccnz .LBB0_330
	s_mov_b64 s[4:5], 0
